# adaLN norm loop body rewritten: all parameter loads issued up front, one wait, both rows reduced together
# baseline (speedup 1.0000x reference)
; DEVI unsigned cvt_pk_bf16(float lo, float hi) { unsigned r; asm volatile("v_cvt_pk_bf16_f32 %0, %1, %2" : "=v"(r) : "v"(lo), "v"(hi)); return r; }
; DEVI const float* modrow(const Params& p, int l, int row) { const int bi = row < NLAT ? (row >> 11) : 16; return (const float*)(p.ws + OFF_MOD) + (size_t)(l * 17 + bi) * 6144; }
; DEVI void ph_norm(const int wv, const Params& p, int l, int which  , int nrows) {
;     ...
;     for (int row0 = blockIdx.x * 8 + wave; row0 < nrows; row0 += 2 * stride) {
;         f32x4 v[2][4]; float ss[2];
; #pragma unroll
;         for (int q = 0; q < 2; ++q) { const int row = row0 + q * stride; ss[q] = 0.f;
;             if (row < nrows) { const float* x = which ? (const float*)xrow_out(p, row) : xrow_in(p, l, row);
; #pragma unroll
;                 for (int i = 0; i < 4; ++i) v[q][i] = *(const f32x4*)(x + i * 256 + lane * 4); }
;             else {
; #pragma unroll
;                 for (int i = 0; i < 4; ++i) v[q][i] = (f32x4){0.f, 0.f, 0.f, 0.f}; } }
; #pragma unroll
;         for (int q = 0; q < 2; ++q) {
; #pragma unroll
;             for (int i = 0; i < 4; ++i) ss[q] += v[q][i][0] * v[q][i][0] + v[q][i][1] * v[q][i][1] + v[q][i][2] * v[q][i][2] + v[q][i][3] * v[q][i][3];
;             ss[q] = wsum(ss[q]); }
; #pragma unroll
;         for (int q = 0; q < 2; ++q) { const int row = row0 + q * stride;
;             if (row < nrows) { const float* md = modrow(p, l, row); const float rstd = rsqrtf(ss[q] * (1.0f / 1024.0f) + EPS);
; #pragma unroll
;                 for (int i = 0; i < 4; ++i) { const int c = i * 256 + lane * 4;
;                     const f32x4 w = *(const f32x4*)(nw + c), sc = *(const f32x4*)(md + scoff + c), sh = *(const f32x4*)(md + shoff + c);
;                     const f32x4 o = v[q][i] * rstd * w * (1.0f + sc) + sh;
;                     u32x2 pk; pk.x = cvt_pk_bf16(o[0], o[1]); pk.y = cvt_pk_bf16(o[2], o[3]);
;                     *(u32x2*)(U + (size_t)row * 1024 + c) = pk; } } }
;     }
.LBB0_211:
	s_min_i32 s0, s31, 0x8000
	s_ashr_i32 s0, s0, 11
	s_add_i32 s0, s0, s30
	s_mul_hi_i32 s1, s0, 0x6000
	s_mulk_i32 s0, 0x6000
	s_add_u32 s0, s36, s0
	s_addc_u32 s1, s37, s1
	s_add_u32 s8, s0, 0x1000
	s_addc_u32 s9, s1, 0
	global_load_dwordx4 v[68:71], v[36:37], off
	global_load_dwordx4 v[72:75], v[36:37], off offset:1024
	global_load_dwordx4 v[76:79], v[36:37], off offset:2048
	global_load_dwordx4 v[80:83], v[36:37], off offset:3072
	global_load_dwordx4 v[84:87], v0, s[8:9]
	global_load_dwordx4 v[88:91], v0, s[8:9] offset:1024
	global_load_dwordx4 v[92:95], v0, s[8:9] offset:2048
	global_load_dwordx4 v[96:99], v0, s[8:9] offset:3072
	global_load_dwordx4 v[100:103], v0, s[0:1]
	global_load_dwordx4 v[104:107], v0, s[0:1] offset:1024
	global_load_dwordx4 v[108:111], v0, s[0:1] offset:2048
	global_load_dwordx4 v[112:115], v0, s[0:1] offset:3072
	s_andn2_b64 vcc, exec, s[6:7]
	s_cbranch_vccnz .Lnorm_noload1
	s_min_i32 s10, s4, 0x8000
	s_ashr_i32 s10, s10, 11
	s_add_i32 s10, s10, s30
	s_mul_hi_i32 s11, s10, 0x6000
	s_mulk_i32 s10, 0x6000
	s_add_u32 s10, s36, s10
	s_addc_u32 s11, s37, s11
	s_add_u32 s12, s10, 0x1000
	s_addc_u32 s13, s11, 0
	global_load_dwordx4 v[140:143], v0, s[12:13]
	global_load_dwordx4 v[144:147], v0, s[12:13] offset:1024
	global_load_dwordx4 v[148:151], v0, s[12:13] offset:2048
	global_load_dwordx4 v[152:155], v0, s[12:13] offset:3072
	global_load_dwordx4 v[156:159], v0, s[10:11]
	global_load_dwordx4 v[160:163], v0, s[10:11] offset:1024
	global_load_dwordx4 v[164:167], v0, s[10:11] offset:2048
	global_load_dwordx4 v[168:171], v0, s[10:11] offset:3072
.Lnorm_noload1:
	s_ashr_i32 s29, s4, 31
	s_mov_b32 s28, s4
	s_lshl_b64 s[28:29], s[28:29], 11
	s_mov_b32 s5, 0x800000
	s_waitcnt vmcnt(0)
	v_lshl_add_u64 v[116:117], v[44:45], 0, s[28:29]
	v_mul_f32_e32 v50, v30, v30
	v_mul_f32_e32 v52, v31, v31
	v_fmac_f32_e32 v50, v32, v32
	v_fmac_f32_e32 v52, v33, v33
	v_fmac_f32_e32 v50, v26, v26
	v_fmac_f32_e32 v52, v27, v27
	v_fmac_f32_e32 v50, v28, v28
	v_fmac_f32_e32 v52, v29, v29
	v_fmac_f32_e32 v50, v22, v22
	v_fmac_f32_e32 v52, v23, v23
	v_fmac_f32_e32 v50, v24, v24
	v_fmac_f32_e32 v52, v25, v25
	v_fmac_f32_e32 v50, v2, v2
	v_fmac_f32_e32 v52, v3, v3
	v_fmac_f32_e32 v50, v4, v4
	v_fmac_f32_e32 v52, v5, v5
	v_add_f32_e32 v50, v50, v52
	v_mul_f32_e32 v51, v18, v18
	v_mul_f32_e32 v53, v19, v19
	v_fmac_f32_e32 v51, v20, v20
	v_fmac_f32_e32 v53, v21, v21
	v_fmac_f32_e32 v51, v14, v14
	v_fmac_f32_e32 v53, v15, v15
	v_fmac_f32_e32 v51, v16, v16
	v_fmac_f32_e32 v53, v17, v17
	v_fmac_f32_e32 v51, v10, v10
	v_fmac_f32_e32 v53, v11, v11
	v_fmac_f32_e32 v51, v12, v12
	v_fmac_f32_e32 v53, v13, v13
	v_fmac_f32_e32 v51, v6, v6
	v_fmac_f32_e32 v53, v7, v7
	v_fmac_f32_e32 v51, v8, v8
	v_fmac_f32_e32 v53, v9, v9
	v_add_f32_e32 v51, v51, v53
	ds_bpermute_b32 v54, v35, v50
	ds_bpermute_b32 v55, v35, v51
	s_waitcnt lgkmcnt(0)
	v_add_f32_e32 v50, v50, v54
	v_add_f32_e32 v51, v51, v55
	ds_bpermute_b32 v54, v39, v50
	ds_bpermute_b32 v55, v39, v51
	s_waitcnt lgkmcnt(0)
	v_add_f32_e32 v50, v50, v54
	v_add_f32_e32 v51, v51, v55
	ds_bpermute_b32 v54, v41, v50
	ds_bpermute_b32 v55, v41, v51
	s_waitcnt lgkmcnt(0)
	v_add_f32_e32 v50, v50, v54
	v_add_f32_e32 v51, v51, v55
	ds_bpermute_b32 v54, v43, v50
	ds_bpermute_b32 v55, v43, v51
	s_waitcnt lgkmcnt(0)
	v_add_f32_e32 v50, v50, v54
	v_add_f32_e32 v51, v51, v55
	ds_bpermute_b32 v54, v48, v50
	ds_bpermute_b32 v55, v48, v51
	s_waitcnt lgkmcnt(0)
	v_add_f32_e32 v50, v50, v54
	v_add_f32_e32 v51, v51, v55
	ds_bpermute_b32 v54, v49, v50
	ds_bpermute_b32 v55, v49, v51
	s_waitcnt lgkmcnt(0)
	v_add_f32_e32 v50, v50, v54
	v_add_f32_e32 v51, v51, v55
	v_fmamk_f32 v50, v50, 0x3a800000, v196
	v_mul_f32_e32 v54, 0x4b800000, v50
	v_cmp_gt_f32_e32 vcc, s5, v50
	s_nop 1
	v_cndmask_b32_e32 v50, v50, v54, vcc
	v_rsq_f32_e32 v50, v50
	s_nop 0
	v_mul_f32_e32 v54, 0x45800000, v50
	v_cndmask_b32_e32 v50, v50, v54, vcc
	v_fmamk_f32 v51, v51, 0x3a800000, v196
	v_mul_f32_e32 v55, 0x4b800000, v51
	v_cmp_gt_f32_e32 vcc, s5, v51
	s_nop 1
	v_cndmask_b32_e32 v51, v51, v55, vcc
	v_rsq_f32_e32 v51, v51
	s_nop 0
	v_mul_f32_e32 v55, 0x45800000, v51
	v_cndmask_b32_e32 v51, v51, v55, vcc
	v_mov_b32_e32 v56, v51
	v_pk_mul_f32 v[30:31], v[30:31], v[50:51] op_sel_hi:[1,0]
	v_pk_mul_f32 v[32:33], v[32:33], v[50:51] op_sel_hi:[1,0]
	v_pk_mul_f32 v[30:31], v[68:69], v[30:31]
	v_pk_mul_f32 v[32:33], v[70:71], v[32:33]
	v_pk_add_f32 v[118:119], v[84:85], 1.0 op_sel_hi:[1,0]
	v_pk_add_f32 v[120:121], v[86:87], 1.0 op_sel_hi:[1,0]
	v_pk_fma_f32 v[30:31], v[118:119], v[30:31], v[100:101]
	v_pk_fma_f32 v[32:33], v[120:121], v[32:33], v[102:103]
	v_cvt_pk_bf16_f32 v118, v30, v31
	v_cvt_pk_bf16_f32 v119, v32, v33
	global_store_dwordx2 v[46:47], v[118:119], off
	v_pk_mul_f32 v[26:27], v[26:27], v[50:51] op_sel_hi:[1,0]
	v_pk_mul_f32 v[28:29], v[28:29], v[50:51] op_sel_hi:[1,0]
	v_pk_mul_f32 v[26:27], v[72:73], v[26:27]
	v_pk_mul_f32 v[28:29], v[74:75], v[28:29]
	v_pk_add_f32 v[122:123], v[88:89], 1.0 op_sel_hi:[1,0]
	v_pk_add_f32 v[124:125], v[90:91], 1.0 op_sel_hi:[1,0]
	v_pk_fma_f32 v[26:27], v[122:123], v[26:27], v[104:105]
	v_pk_fma_f32 v[28:29], v[124:125], v[28:29], v[106:107]
	v_cvt_pk_bf16_f32 v122, v26, v27
	v_cvt_pk_bf16_f32 v123, v28, v29
	global_store_dwordx2 v[46:47], v[122:123], off offset:512
	v_pk_mul_f32 v[22:23], v[22:23], v[50:51] op_sel_hi:[1,0]
	v_pk_mul_f32 v[24:25], v[24:25], v[50:51] op_sel_hi:[1,0]
	v_pk_mul_f32 v[22:23], v[76:77], v[22:23]
	v_pk_mul_f32 v[24:25], v[78:79], v[24:25]
	v_pk_add_f32 v[126:127], v[92:93], 1.0 op_sel_hi:[1,0]
	v_pk_add_f32 v[128:129], v[94:95], 1.0 op_sel_hi:[1,0]
	v_pk_fma_f32 v[22:23], v[126:127], v[22:23], v[108:109]
	v_pk_fma_f32 v[24:25], v[128:129], v[24:25], v[110:111]
	v_cvt_pk_bf16_f32 v126, v22, v23
	v_cvt_pk_bf16_f32 v127, v24, v25
	global_store_dwordx2 v[46:47], v[126:127], off offset:1024
	v_pk_mul_f32 v[2:3], v[2:3], v[50:51] op_sel_hi:[1,0]
	v_pk_mul_f32 v[4:5], v[4:5], v[50:51] op_sel_hi:[1,0]
	v_pk_mul_f32 v[2:3], v[80:81], v[2:3]
	v_pk_mul_f32 v[4:5], v[82:83], v[4:5]
	v_pk_add_f32 v[130:131], v[96:97], 1.0 op_sel_hi:[1,0]
	v_pk_add_f32 v[132:133], v[98:99], 1.0 op_sel_hi:[1,0]
	v_pk_fma_f32 v[2:3], v[130:131], v[2:3], v[112:113]
	v_pk_fma_f32 v[4:5], v[132:133], v[4:5], v[114:115]
	v_cvt_pk_bf16_f32 v130, v2, v3
	v_cvt_pk_bf16_f32 v131, v4, v5
	global_store_dwordx2 v[46:47], v[130:131], off offset:1536
	s_andn2_b64 vcc, exec, s[6:7]
	s_cbranch_vccnz .LBB0_186
; DEVI unsigned cvt_pk_bf16(float lo, float hi) { unsigned r; asm volatile("v_cvt_pk_bf16_f32 %0, %1, %2" : "=v"(r) : "v"(lo), "v"(hi)); return r; }
; DEVI const float* modrow(const Params& p, int l, int row) { const int bi = row < NLAT ? (row >> 11) : 16; return (const float*)(p.ws + OFF_MOD) + (size_t)(l * 17 + bi) * 6144; }
; DEVI void ph_norm(const int wv, const Params& p, int l, int which  , int nrows) {
;     ...
;         for (int q = 0; q < 2; ++q) { const int row = row0 + q * stride;
;             if (row < nrows) { const float* md = modrow(p, l, row); const float rstd = rsqrtf(ss[q] * (1.0f / 1024.0f) + EPS);
; #pragma unroll
;                 for (int i = 0; i < 4; ++i) { const int c = i * 256 + lane * 4;
;                     const f32x4 w = *(const f32x4*)(nw + c), sc = *(const f32x4*)(md + scoff + c), sh = *(const f32x4*)(md + shoff + c);
;                     const f32x4 o = v[q][i] * rstd * w * (1.0f + sc) + sh;
;                     u32x2 pk; pk.x = cvt_pk_bf16(o[0], o[1]); pk.y = cvt_pk_bf16(o[2], o[3]);
;                     *(u32x2*)(U + (size_t)row * 1024 + c) = pk; } } }
	v_pk_mul_f32 v[18:19], v[18:19], v[56:57] op_sel_hi:[1,0]
	v_pk_mul_f32 v[20:21], v[20:21], v[56:57] op_sel_hi:[1,0]
	v_pk_mul_f32 v[18:19], v[68:69], v[18:19]
	v_pk_mul_f32 v[20:21], v[70:71], v[20:21]
	v_pk_add_f32 v[172:173], v[140:141], 1.0 op_sel_hi:[1,0]
	v_pk_add_f32 v[174:175], v[142:143], 1.0 op_sel_hi:[1,0]
	v_pk_fma_f32 v[18:19], v[172:173], v[18:19], v[156:157]
	v_pk_fma_f32 v[20:21], v[174:175], v[20:21], v[158:159]
	v_cvt_pk_bf16_f32 v172, v18, v19
	v_cvt_pk_bf16_f32 v173, v20, v21
	global_store_dwordx2 v[116:117], v[172:173], off
	v_pk_mul_f32 v[14:15], v[14:15], v[56:57] op_sel_hi:[1,0]
	v_pk_mul_f32 v[16:17], v[16:17], v[56:57] op_sel_hi:[1,0]
	v_pk_mul_f32 v[14:15], v[72:73], v[14:15]
	v_pk_mul_f32 v[16:17], v[74:75], v[16:17]
	v_pk_add_f32 v[176:177], v[144:145], 1.0 op_sel_hi:[1,0]
	v_pk_add_f32 v[178:179], v[146:147], 1.0 op_sel_hi:[1,0]
	v_pk_fma_f32 v[14:15], v[176:177], v[14:15], v[160:161]
	v_pk_fma_f32 v[16:17], v[178:179], v[16:17], v[162:163]
	v_cvt_pk_bf16_f32 v176, v14, v15
	v_cvt_pk_bf16_f32 v177, v16, v17
	global_store_dwordx2 v[116:117], v[176:177], off offset:512
	v_pk_mul_f32 v[10:11], v[10:11], v[56:57] op_sel_hi:[1,0]
	v_pk_mul_f32 v[12:13], v[12:13], v[56:57] op_sel_hi:[1,0]
	v_pk_mul_f32 v[10:11], v[76:77], v[10:11]
	v_pk_mul_f32 v[12:13], v[78:79], v[12:13]
	v_pk_add_f32 v[180:181], v[148:149], 1.0 op_sel_hi:[1,0]
	v_pk_add_f32 v[182:183], v[150:151], 1.0 op_sel_hi:[1,0]
	v_pk_fma_f32 v[10:11], v[180:181], v[10:11], v[164:165]
	v_pk_fma_f32 v[12:13], v[182:183], v[12:13], v[166:167]
	v_cvt_pk_bf16_f32 v180, v10, v11
	v_cvt_pk_bf16_f32 v181, v12, v13
	global_store_dwordx2 v[116:117], v[180:181], off offset:1024
	v_pk_mul_f32 v[6:7], v[6:7], v[56:57] op_sel_hi:[1,0]
	v_pk_mul_f32 v[8:9], v[8:9], v[56:57] op_sel_hi:[1,0]
	v_pk_mul_f32 v[6:7], v[80:81], v[6:7]
	v_pk_mul_f32 v[8:9], v[82:83], v[8:9]
	v_pk_add_f32 v[184:185], v[152:153], 1.0 op_sel_hi:[1,0]
	v_pk_add_f32 v[186:187], v[154:155], 1.0 op_sel_hi:[1,0]
	v_pk_fma_f32 v[6:7], v[184:185], v[6:7], v[168:169]
	v_pk_fma_f32 v[8:9], v[186:187], v[8:9], v[170:171]
	v_cvt_pk_bf16_f32 v184, v6, v7
	v_cvt_pk_bf16_f32 v185, v8, v9
	global_store_dwordx2 v[116:117], v[184:185], off offset:1536
	s_branch .LBB0_186

; DEVI int opaque_tid(int wv) { int ln; asm volatile("v_mbcnt_lo_u32_b32 %0, -1, 0\n\tv_mbcnt_hi_u32_b32 %0, -1, %0" : "=v"(ln)); return wv * 64 + ln; }
;     DEVI bool next(int i, Unit& u) const {
;         const int ti = i / nb; u.pb = i - ti * nb;
;         const long L = (long)ti * G + c;
;         if (L >= nwg) { const int t = (int)(L - nwg); if (t >= tail_units) return false; u.pm = nM + t / tail_nN; u.pn = t % tail_nN; return true; }
; template <class Epi>
; DEVI void gemm_phase(const int wv, LAS unsigned char* lds, const Gemm g, const Order& S, const Epi& E) {
;     const int tid = opaque_tid(wv), wid = wv, lane = tid & 63, wr = wid >> 2, wc = wid & 3, fr = lane & 15, fq = lane >> 4;
;     const int K = g.K, nt = K / BK;
;     unsigned voffA[2], voffB[2];
; #pragma unroll
;     for (int i = 0; i < 2; ++i) { int R, C; stage_rc(tid * 16 + i * 8192, R, C); const int Rb = Epi::PERM ? ((R & ~31) + perm32(R & 31)) : R;
;         voffA[i] = (unsigned)(R * g.lda + C) * 2u; voffB[i] = (unsigned)(Rb * g.ldb + C) * 2u; }
;     const size_t kstep = (size_t)(BK * 2);
;     const size_t hstepA = (size_t)HALF * g.lda * 2, hstepB = (size_t)HALF * g.ldb * 2;
;     const size_t tstepA = 2 * hstepA, tstepB = 2 * hstepB;
;     const unsigned ldsw = (unsigned)wid * 1024u;
;     const int aoff = lds_byte(wr * 64 + fr, fq * 8), boff = lds_byte(wc * 32 + fr, fq * 8);
;     ...
;     Unit cur, nxt; int ui = 0;
;     if (!S.next(0, cur)) return;
;     f32x4 acc[2][2][4][2];
; #pragma unroll
;     for (int a = 0; a < 2; ++a)
; #pragma unroll
;         for (int b = 0; b < 2; ++b)
; #pragma unroll
;             for (int m = 0; m < 4; ++m)
; #pragma unroll
;                 for (int n = 0; n < 2; ++n) acc[a][b][m][n] = (f32x4){0.f, 0.f, 0.f, 0.f};
;     bf16x8 At[4][2], B0[2][2], B1[2][2];
;     const char* cA = (const char*)g.A + (size_t)cur.pb * g.a_bs + (size_t)cur.pm * tstepA; const char* cB = (const char*)g.Bt + (size_t)cur.pb * g.b_bs + (size_t)cur.pn * tstepB;
;     PG8_STAGE(PG8_SB(0, 0), cB, voffB); PG8_STAGE(PG8_SA(0, 0), cA, voffA); PG8_STAGE(PG8_SB(0, 1), cB + hstepB, voffB); PG8_STAGE(PG8_SA(0, 1), cA + hstepA, voffA);
;     if (wr == 1) PG8_BAR;
;     PG8_WAIT_V(4); PG8_BAR;
;     PG8_STAGE(PG8_SB(1, 0), cB + kstep, voffB); PG8_STAGE(PG8_SA(1, 0), cA + kstep, voffA); PG8_STAGE(PG8_SB(1, 1), cB + hstepB + kstep, voffB);
;     PG8_WAIT_V(6); PG8_BAR;
.LBB0_280:
	v_lshl_add_u64 v[8:9], v[8:9], 0, s[92:93]
	s_add_i32 m0, s1, 0x18000
	s_waitcnt vmcnt(4)
	s_barrier
	global_load_lds_dwordx4 v[8:9], off
	v_lshl_add_u64 v[4:5], v[4:5], 0, s[92:93]
	s_add_i32 m0, s1, 0x1a000
	s_add_i32 s51, s1, 0x8000
	s_add_i32 s52, s1, 0xa000
	global_load_lds_dwordx4 v[4:5], off
	v_lshl_add_u64 v[2:3], v[2:3], 0, s[92:93]
	s_mov_b32 m0, s51
	s_add_u32 s4, s30, 0x40080
	global_load_lds_dwordx4 v[2:3], off
	v_lshl_add_u64 v[2:3], v[6:7], 0, s[92:93]
	s_mov_b32 m0, s52
	s_addc_u32 s5, s31, 0
	global_load_lds_dwordx4 v[2:3], off
	v_lshl_add_u64 v[2:3], s[4:5], 0, v[0:1]
	s_add_i32 m0, s1, 0x1c000
	s_lshr_b32 s53, s18, 3
	global_load_lds_dwordx4 v[2:3], off
	v_lshl_add_u64 v[2:3], s[4:5], 0, v[134:135]
	s_add_i32 m0, s1, 0x1e000
	v_readlane_b32 s4, v252, 6
	global_load_lds_dwordx4 v[2:3], off
	v_and_b32_e32 v2, 15, v10
	v_lshrrev_b32_e32 v3, 1, v10
	v_or_b32_e32 v144, s4, v2
	v_and_b32_e32 v3, 24, v3
	v_lshlrev_b32_e32 v4, 6, v144
	v_lshlrev_b32_e32 v5, 1, v3
	s_movk_i32 s4, 0x3c0
	v_lshlrev_b32_e32 v6, 2, v144
	v_and_or_b32 v4, v4, s4, v5
	v_and_b32_e32 v6, 32, v6
	v_readlane_b32 s4, v252, 7
	v_lshl_or_b32 v2, v2, 6, v5
	v_lshlrev_b32_e32 v5, 2, v10
	v_bitop3_b32 v4, v4, s4, v6 bitop3:0xde
	v_and_b32_e32 v5, 32, v5
	v_readlane_b32 s4, v252, 9
	s_waitcnt vmcnt(6)
	s_mov_b32 s54, 0
	v_mov_b32_e32 v137, v1
	v_bitop3_b32 v145, v2, s4, v5 bitop3:0xde
	v_cvt_f32_ubyte0_e32 v2, s40
	v_rcp_iflag_f32_e32 v2, v2
	v_readlane_b32 s4, v252, 8
	v_mov_b32_e32 v139, v1
	v_add_u32_e32 v147, 0, v4
	v_mul_f32_e32 v2, 0x4f7ffffe, v2
	v_cvt_u32_f32_e32 v2, v2
	v_or_b32_e32 v146, s4, v3
	v_and_b32_e32 v3, 1, v11
	s_sub_i32 s4, 0, s40
	v_readfirstlane_b32 s5, v2
	v_lshlrev_b32_e32 v2, 14, v11
	v_and_b32_e32 v2, 0xffff8000, v2
	v_lshl_add_u32 v2, v12, 11, v2
	v_lshl_or_b32 v2, v3, 6, v2
	v_lshl_add_u32 v136, v13, 1, v2
	v_lshlrev_b32_e32 v2, 14, v14
	v_and_b32_e32 v2, 0xffff8000, v2
	s_mul_i32 s4, s4, s5
	v_lshl_add_u32 v2, v15, 11, v2
	v_and_b32_e32 v3, 1, v14
	s_mul_hi_u32 s4, s5, s4
	v_lshl_or_b32 v2, v3, 6, v2
	s_add_i32 s55, s5, s4
	v_lshl_add_u32 v138, v16, 1, v2
	s_barrier
.LBB0_281:
	s_add_i32 s54, s54, 1
	v_readlane_b32 s5, v252, 12
	s_mul_i32 s5, s54, s5
	s_mul_hi_u32 s7, s54, s33
	s_add_i32 s7, s7, s5
	s_mul_i32 s5, s54, s33
	v_readlane_b32 s8, v253, 12
	s_add_u32 s8, s5, s8
	v_readlane_b32 s5, v252, 4
	s_addc_u32 s9, s7, s5
	v_mov_b64_e32 v[2:3], s[18:19]
	v_cmp_lt_i64_e32 vcc, s[8:9], v[2:3]
	s_mov_b64 s[10:11], -1
	s_cbranch_vccnz .LBB0_284
	s_sub_i32 s5, s8, s18
	s_mov_b64 s[10:11], 0
	s_cmp_ge_i32 s5, s39
	s_mov_b64 s[36:37], 0
	s_cbranch_scc1 .LBB0_284
	s_abs_i32 s6, s5
	s_mul_hi_u32 s7, s6, s55
	s_mul_i32 s9, s7, s40
	s_sub_i32 s6, s6, s9
	s_ashr_i32 s4, s5, 31
	s_add_i32 s9, s7, 1
	s_sub_i32 s12, s6, s40
	s_cmp_ge_u32 s6, s40
	s_cselect_b32 s7, s9, s7
	s_cselect_b32 s6, s12, s6
	s_add_i32 s9, s7, 1
	s_cmp_ge_u32 s6, s40
	s_cselect_b32 s6, s9, s7
	s_xor_b32 s6, s6, s4
	s_sub_i32 s4, s6, s4
	s_add_i32 s6, s4, s38
	s_mul_i32 s4, s4, s40
	s_sub_i32 s4, s5, s4
	s_mov_b64 s[36:37], -1

; #define PG8_STAGE(bufoff, gbase, voff) do { _Pragma("unroll") for (int _i = 0; _i < 2; ++_i) \
;         __builtin_amdgcn_global_load_lds((const unsigned*)((const char*)(gbase) + (voff)[_i]), (LAS unsigned*)(lds + (bufoff) + ldsw + _i * 8192), 16, 0, 0); } while (0)
; #define PG8_LDA(dst, b, h) do { _Pragma("unroll") for (int m = 0; m < 4; ++m) _Pragma("unroll") for (int k = 0; k < 2; ++k) dst[m][k] = *(const LAS bf16x8*)(lds + PG8_SA(b, h) + aoff + m * 2048 + k * 1024); } while (0)
; #define PG8_LDB(dst, b, h) do { _Pragma("unroll") for (int n = 0; n < 2; ++n) _Pragma("unroll") for (int k = 0; k < 2; ++k) dst[n][k] = *(const LAS bf16x8*)(lds + PG8_SB(b, h) + boff + n * 2048 + k * 1024); } while (0)
; #define PG8_MMA(ai, bj, At, Bt) do { __builtin_amdgcn_s_setprio(1); _Pragma("unroll") for (int m = 0; m < 4; ++m) _Pragma("unroll") for (int n = 0; n < 2; ++n) _Pragma("unroll") for (int k = 0; k < 2; ++k) \
;         acc[ai][bj][m][n] = __builtin_amdgcn_mfma_f32_16x16x32_bf16(Bt[n][k], At[m][k], acc[ai][bj][m][n], 0, 0, 0); __builtin_amdgcn_s_setprio(0); } while (0)
; #define PG8_WAIT_V(n) asm volatile("s_waitcnt vmcnt(" #n ")" ::: "memory")
; #define PG8_WAIT_L(n) asm volatile("s_waitcnt lgkmcnt(" #n ")" ::: "memory")
; #define PG8_BAR __builtin_amdgcn_s_barrier()
; #define PG8_SCHED __builtin_amdgcn_sched_barrier(0)
; template <class Epi>
; DEVI void gemm_phase(const int wv, LAS unsigned char* lds, const Gemm g, const Order& S, const Epi& E) {
;     ...
;             PG8_LDB(B0, 0, 0); PG8_SCHED; PG8_LDA(At, 0, 0); PG8_STAGE(PG8_SA(1, 1), a1 + hstepA, voffA);
;             PG8_WAIT_L(8); PG8_BAR; PG8_WAIT_L(0); PG8_MMA(0, 0, At, B0); PG8_BAR; PG8_SCHED;
;             PG8_LDB(B1, 0, 1); PG8_STAGE(PG8_SB(0, 0), b2, voffB);
;             PG8_BAR; PG8_WAIT_L(0); PG8_MMA(0, 1, At, B1); PG8_BAR;
;             PG8_LDA(At, 0, 1); PG8_STAGE(PG8_SA(0, 0), a2, voffA);
;             PG8_BAR; PG8_WAIT_L(0); PG8_MMA(1, 0, At, B0); PG8_BAR; PG8_SCHED;
;             PG8_STAGE(PG8_SB(0, 1), b2 + hstepB, voffB);
;             PG8_WAIT_V(6); PG8_BAR; PG8_MMA(1, 1, At, B1); PG8_BAR;
.LBB0_287:
	s_add_u32 s30, s28, 0xfffc0080
	s_addc_u32 s31, s29, -1
	s_add_i32 s61, 0, 0x10000
	v_add_u32_e32 v156, s61, v145
	ds_read_b128 v[140:143], v156
	ds_read_b128 v[148:151], v156 offset:1024
	ds_read_b128 v[152:155], v156 offset:2048
	ds_read_b128 v[156:159], v156 offset:3072
	s_cmp_eq_u32 s60, 12
	s_cselect_b32 s37, s7, s31
	s_cselect_b32 s36, s56, s30
	s_cselect_b32 s31, s5, s59
	s_cselect_b32 s30, s57, s58
	v_lshl_add_u64 v[192:193], s[28:29], 0, v[136:137]
	s_add_i32 m0, s1, 0xc000
	ds_read_b128 v[160:163], v147
	ds_read_b128 v[164:167], v147 offset:1024
	ds_read_b128 v[168:171], v147 offset:2048
	ds_read_b128 v[172:175], v147 offset:3072
	ds_read_b128 v[176:179], v147 offset:4096
	ds_read_b128 v[180:183], v147 offset:5120
	ds_read_b128 v[184:187], v147 offset:6144
	ds_read_b128 v[188:191], v147 offset:7168
	global_load_lds_dwordx4 v[192:193], off
	v_lshl_add_u64 v[192:193], s[28:29], 0, v[138:139]
	s_add_i32 m0, s1, 0xe000
	s_nop 0
	global_load_lds_dwordx4 v[192:193], off
	s_waitcnt lgkmcnt(8)
	s_barrier
	s_waitcnt lgkmcnt(0)
	s_setprio 1
	s_waitcnt lgkmcnt(0)
	v_mfma_f32_16x16x32_bf16 v[126:129], v[140:143], v[160:163], v[126:129]
	v_mfma_f32_16x16x32_bf16 v[122:125], v[152:155], v[160:163], v[122:125]
	v_mfma_f32_16x16x32_bf16 v[118:121], v[140:143], v[168:171], v[118:121]
	v_mfma_f32_16x16x32_bf16 v[110:113], v[152:155], v[168:171], v[110:113]
	v_mfma_f32_16x16x32_bf16 v[102:105], v[140:143], v[176:179], v[102:105]
	v_mfma_f32_16x16x32_bf16 v[94:97], v[152:155], v[176:179], v[94:97]
	v_mfma_f32_16x16x32_bf16 v[86:89], v[140:143], v[184:187], v[86:89]
	v_mfma_f32_16x16x32_bf16 v[78:81], v[152:155], v[184:187], v[78:81]
	v_mfma_f32_16x16x32_bf16 v[126:129], v[148:151], v[164:167], v[126:129]
	v_mfma_f32_16x16x32_bf16 v[122:125], v[156:159], v[164:167], v[122:125]
	v_mfma_f32_16x16x32_bf16 v[118:121], v[148:151], v[172:175], v[118:121]
	v_mfma_f32_16x16x32_bf16 v[110:113], v[156:159], v[172:175], v[110:113]
	v_mfma_f32_16x16x32_bf16 v[102:105], v[148:151], v[180:183], v[102:105]
	v_mfma_f32_16x16x32_bf16 v[94:97], v[156:159], v[180:183], v[94:97]
	v_mfma_f32_16x16x32_bf16 v[86:89], v[148:151], v[188:191], v[86:89]
	v_mfma_f32_16x16x32_bf16 v[78:81], v[156:159], v[188:191], v[78:81]
	s_setprio 0
	s_barrier
	s_add_i32 s64, 0, 0x14000
	s_add_i32 s61, s61, s95
	v_add_u32_e32 v199, s64, v145
	v_lshl_add_u64 v[212:213], s[30:31], 0, v[0:1]
	s_mov_b32 m0, s61
	ds_read_b128 v[192:195], v199
	ds_read_b128 v[200:203], v199 offset:1024
	ds_read_b128 v[204:207], v199 offset:2048
	ds_read_b128 v[208:211], v199 offset:3072
	global_load_lds_dwordx4 v[212:213], off
	v_lshl_add_u64 v[214:215], s[30:31], 0, v[134:135]
	s_add_i32 m0, s61, 0x2000
	s_nop 0
	global_load_lds_dwordx4 v[214:215], off
	s_barrier
	s_waitcnt lgkmcnt(0)
	s_setprio 1
	s_waitcnt lgkmcnt(0)
	v_mfma_f32_16x16x32_bf16 v[114:117], v[192:195], v[160:163], v[114:117]
	v_mfma_f32_16x16x32_bf16 v[106:109], v[204:207], v[160:163], v[106:109]
	v_mfma_f32_16x16x32_bf16 v[98:101], v[192:195], v[168:171], v[98:101]
	v_mfma_f32_16x16x32_bf16 v[90:93], v[204:207], v[168:171], v[90:93]
	v_mfma_f32_16x16x32_bf16 v[82:85], v[192:195], v[176:179], v[82:85]
	v_mfma_f32_16x16x32_bf16 v[74:77], v[204:207], v[176:179], v[74:77]
	v_mfma_f32_16x16x32_bf16 v[70:73], v[192:195], v[184:187], v[70:73]
	v_mfma_f32_16x16x32_bf16 v[66:69], v[204:207], v[184:187], v[66:69]
	v_mfma_f32_16x16x32_bf16 v[114:117], v[200:203], v[164:167], v[114:117]
	v_mfma_f32_16x16x32_bf16 v[106:109], v[208:211], v[164:167], v[106:109]
	v_mfma_f32_16x16x32_bf16 v[98:101], v[200:203], v[172:175], v[98:101]
	v_mfma_f32_16x16x32_bf16 v[90:93], v[208:211], v[172:175], v[90:93]
	v_mfma_f32_16x16x32_bf16 v[82:85], v[200:203], v[180:183], v[82:85]
	v_mfma_f32_16x16x32_bf16 v[74:77], v[208:211], v[180:183], v[74:77]
	v_mfma_f32_16x16x32_bf16 v[70:73], v[200:203], v[188:191], v[70:73]
	v_mfma_f32_16x16x32_bf16 v[66:69], v[208:211], v[188:191], v[66:69]
	s_setprio 0
	s_mov_b32 m0, s1
	v_lshl_add_u64 v[216:217], s[36:37], 0, v[130:131]
	s_barrier
	ds_read_b128 v[160:163], v147 offset:16384
	ds_read_b128 v[164:167], v147 offset:17408
	ds_read_b128 v[168:171], v147 offset:18432
	ds_read_b128 v[172:175], v147 offset:19456
	ds_read_b128 v[176:179], v147 offset:20480
	ds_read_b128 v[180:183], v147 offset:21504
	ds_read_b128 v[184:187], v147 offset:22528
	ds_read_b128 v[188:191], v147 offset:23552
	global_load_lds_dwordx4 v[216:217], off
	v_lshl_add_u64 v[218:219], s[36:37], 0, v[132:133]
	s_mov_b32 m0, s3
	s_nop 0
	global_load_lds_dwordx4 v[218:219], off
	s_barrier
	s_waitcnt lgkmcnt(0)
	s_setprio 1
	s_waitcnt lgkmcnt(0)
	v_mfma_f32_16x16x32_bf16 v[62:65], v[140:143], v[160:163], v[62:65]
	v_mfma_f32_16x16x32_bf16 v[58:61], v[152:155], v[160:163], v[58:61]
	v_mfma_f32_16x16x32_bf16 v[54:57], v[140:143], v[168:171], v[54:57]
	v_mfma_f32_16x16x32_bf16 v[46:49], v[152:155], v[168:171], v[46:49]
	v_mfma_f32_16x16x32_bf16 v[38:41], v[140:143], v[176:179], v[38:41]
	v_mfma_f32_16x16x32_bf16 v[30:33], v[152:155], v[176:179], v[30:33]
	v_mfma_f32_16x16x32_bf16 v[22:25], v[140:143], v[184:187], v[22:25]
	v_mfma_f32_16x16x32_bf16 v[14:17], v[152:155], v[184:187], v[14:17]
	v_mfma_f32_16x16x32_bf16 v[62:65], v[148:151], v[164:167], v[62:65]
	v_mfma_f32_16x16x32_bf16 v[58:61], v[156:159], v[164:167], v[58:61]
	v_mfma_f32_16x16x32_bf16 v[54:57], v[148:151], v[172:175], v[54:57]
	v_mfma_f32_16x16x32_bf16 v[46:49], v[156:159], v[172:175], v[46:49]
	v_mfma_f32_16x16x32_bf16 v[38:41], v[148:151], v[180:183], v[38:41]
	v_mfma_f32_16x16x32_bf16 v[30:33], v[156:159], v[180:183], v[30:33]
	v_mfma_f32_16x16x32_bf16 v[22:25], v[148:151], v[188:191], v[22:25]
	v_mfma_f32_16x16x32_bf16 v[14:17], v[156:159], v[188:191], v[14:17]
	s_setprio 0
	s_barrier
; #define PG8_STAGE(bufoff, gbase, voff) do { _Pragma("unroll") for (int _i = 0; _i < 2; ++_i) \
;         __builtin_amdgcn_global_load_lds((const unsigned*)((const char*)(gbase) + (voff)[_i]), (LAS unsigned*)(lds + (bufoff) + ldsw + _i * 8192), 16, 0, 0); } while (0)
; #define PG8_LDA(dst, b, h) do { _Pragma("unroll") for (int m = 0; m < 4; ++m) _Pragma("unroll") for (int k = 0; k < 2; ++k) dst[m][k] = *(const LAS bf16x8*)(lds + PG8_SA(b, h) + aoff + m * 2048 + k * 1024); } while (0)
; #define PG8_LDB(dst, b, h) do { _Pragma("unroll") for (int n = 0; n < 2; ++n) _Pragma("unroll") for (int k = 0; k < 2; ++k) dst[n][k] = *(const LAS bf16x8*)(lds + PG8_SB(b, h) + boff + n * 2048 + k * 1024); } while (0)
; #define PG8_MMA(ai, bj, At, Bt) do { __builtin_amdgcn_s_setprio(1); _Pragma("unroll") for (int m = 0; m < 4; ++m) _Pragma("unroll") for (int n = 0; n < 2; ++n) _Pragma("unroll") for (int k = 0; k < 2; ++k) \
;         acc[ai][bj][m][n] = __builtin_amdgcn_mfma_f32_16x16x32_bf16(Bt[n][k], At[m][k], acc[ai][bj][m][n], 0, 0, 0); __builtin_amdgcn_s_setprio(0); } while (0)
; #define PG8_WAIT_V(n) asm volatile("s_waitcnt vmcnt(" #n ")" ::: "memory")
; #define PG8_WAIT_L(n) asm volatile("s_waitcnt lgkmcnt(" #n ")" ::: "memory")
; #define PG8_BAR __builtin_amdgcn_s_barrier()
; #define PG8_SCHED __builtin_amdgcn_sched_barrier(0)
; template <class Epi>
; DEVI void gemm_phase(const int wv, LAS unsigned char* lds, const Gemm g, const Order& S, const Epi& E) {
;     ...
;             PG8_WAIT_V(6); PG8_BAR; PG8_MMA(1, 1, At, B1); PG8_BAR;
;             PG8_LDB(B0, 1, 0); PG8_SCHED; PG8_LDA(At, 1, 0); PG8_STAGE(PG8_SA(0, 1), a2 + hstepA, voffA);
;             PG8_WAIT_L(8); PG8_BAR; PG8_WAIT_L(0); PG8_MMA(0, 0, At, B0); PG8_BAR; PG8_SCHED;
;             PG8_LDB(B1, 1, 1); PG8_STAGE(PG8_SB(1, 0), b3, voffB);
;             PG8_BAR; PG8_WAIT_L(0); PG8_MMA(0, 1, At, B1); PG8_BAR;
;             PG8_LDA(At, 1, 1); PG8_STAGE(PG8_SA(1, 0), a3, voffA);
;             PG8_BAR; PG8_WAIT_L(0); PG8_MMA(1, 0, At, B0); PG8_BAR; PG8_SCHED;
	s_add_u32 s62, s30, 0x40000
	s_addc_u32 s63, s31, 0
	s_add_i32 s61, s64, s95
	v_lshl_add_u64 v[140:141], s[62:63], 0, v[0:1]
	s_mov_b32 m0, s61
	s_nop 0
	global_load_lds_dwordx4 v[140:141], off
	v_lshl_add_u64 v[140:141], s[62:63], 0, v[134:135]
	s_add_i32 m0, s61, 0x2000
	s_nop 0
	global_load_lds_dwordx4 v[140:141], off
	s_waitcnt vmcnt(6)
	s_barrier
	s_setprio 1
	v_mfma_f32_16x16x32_bf16 v[50:53], v[192:195], v[160:163], v[50:53]
	v_mfma_f32_16x16x32_bf16 v[42:45], v[204:207], v[160:163], v[42:45]
	v_mfma_f32_16x16x32_bf16 v[34:37], v[192:195], v[168:171], v[34:37]
	v_mfma_f32_16x16x32_bf16 v[26:29], v[204:207], v[168:171], v[26:29]
	v_mfma_f32_16x16x32_bf16 v[18:21], v[192:195], v[176:179], v[18:21]
	v_mfma_f32_16x16x32_bf16 v[10:13], v[204:207], v[176:179], v[10:13]
	v_mfma_f32_16x16x32_bf16 v[6:9], v[192:195], v[184:187], v[6:9]
	v_mfma_f32_16x16x32_bf16 v[2:5], v[204:207], v[184:187], v[2:5]
	v_mfma_f32_16x16x32_bf16 v[50:53], v[200:203], v[164:167], v[50:53]
	v_mfma_f32_16x16x32_bf16 v[42:45], v[208:211], v[164:167], v[42:45]
	v_mfma_f32_16x16x32_bf16 v[34:37], v[200:203], v[172:175], v[34:37]
	v_mfma_f32_16x16x32_bf16 v[26:29], v[208:211], v[172:175], v[26:29]
	v_mfma_f32_16x16x32_bf16 v[18:21], v[200:203], v[180:183], v[18:21]
	v_mfma_f32_16x16x32_bf16 v[10:13], v[208:211], v[180:183], v[10:13]
	v_mfma_f32_16x16x32_bf16 v[6:9], v[200:203], v[188:191], v[6:9]
	v_mfma_f32_16x16x32_bf16 v[2:5], v[208:211], v[188:191], v[2:5]
	s_setprio 0
	s_add_i32 s61, 0, 0x18000
	v_add_u32_e32 v156, s61, v145
	s_barrier
	ds_read_b128 v[140:143], v156
	ds_read_b128 v[148:151], v156 offset:1024
	ds_read_b128 v[152:155], v156 offset:2048
	ds_read_b128 v[156:159], v156 offset:3072
	s_add_u32 s36, s36, 0x40000
	s_addc_u32 s37, s37, 0
	s_mov_b32 m0, s41
	v_lshl_add_u64 v[192:193], s[36:37], 0, v[130:131]
	ds_read_b128 v[160:163], v147 offset:32768
	ds_read_b128 v[164:167], v147 offset:33792
	ds_read_b128 v[168:171], v147 offset:34816
	ds_read_b128 v[172:175], v147 offset:35840
	ds_read_b128 v[176:179], v147 offset:36864
	ds_read_b128 v[180:183], v147 offset:37888
	ds_read_b128 v[184:187], v147 offset:38912
	ds_read_b128 v[188:191], v147 offset:39936
	global_load_lds_dwordx4 v[192:193], off
	v_lshl_add_u64 v[192:193], s[36:37], 0, v[132:133]
	s_mov_b32 m0, s50
	s_nop 0
	global_load_lds_dwordx4 v[192:193], off
	s_waitcnt lgkmcnt(8)
	s_barrier
	s_waitcnt lgkmcnt(0)
	s_setprio 1
	s_waitcnt lgkmcnt(0)
	v_mfma_f32_16x16x32_bf16 v[126:129], v[140:143], v[160:163], v[126:129]
	v_mfma_f32_16x16x32_bf16 v[122:125], v[152:155], v[160:163], v[122:125]
	v_mfma_f32_16x16x32_bf16 v[118:121], v[140:143], v[168:171], v[118:121]
	v_mfma_f32_16x16x32_bf16 v[110:113], v[152:155], v[168:171], v[110:113]
	v_mfma_f32_16x16x32_bf16 v[102:105], v[140:143], v[176:179], v[102:105]
	v_mfma_f32_16x16x32_bf16 v[94:97], v[152:155], v[176:179], v[94:97]
	v_mfma_f32_16x16x32_bf16 v[86:89], v[140:143], v[184:187], v[86:89]
	v_mfma_f32_16x16x32_bf16 v[78:81], v[152:155], v[184:187], v[78:81]
	v_mfma_f32_16x16x32_bf16 v[126:129], v[148:151], v[164:167], v[126:129]
	v_mfma_f32_16x16x32_bf16 v[122:125], v[156:159], v[164:167], v[122:125]
	v_mfma_f32_16x16x32_bf16 v[118:121], v[148:151], v[172:175], v[118:121]
	v_mfma_f32_16x16x32_bf16 v[110:113], v[156:159], v[172:175], v[110:113]
	v_mfma_f32_16x16x32_bf16 v[102:105], v[148:151], v[180:183], v[102:105]
	v_mfma_f32_16x16x32_bf16 v[94:97], v[156:159], v[180:183], v[94:97]
	v_mfma_f32_16x16x32_bf16 v[86:89], v[148:151], v[188:191], v[86:89]
	v_mfma_f32_16x16x32_bf16 v[78:81], v[156:159], v[188:191], v[78:81]
	s_setprio 0
	s_barrier
	s_add_i32 s36, 0, 0x1c000
	s_add_i32 s37, s61, s95
	v_add_u32_e32 v199, s36, v145
	v_lshl_add_u64 v[212:213], v[212:213], 0, s[92:93]
	s_mov_b32 m0, s37
	ds_read_b128 v[192:195], v199
	ds_read_b128 v[200:203], v199 offset:1024
	ds_read_b128 v[204:207], v199 offset:2048
	ds_read_b128 v[208:211], v199 offset:3072
	global_load_lds_dwordx4 v[212:213], off
	v_lshl_add_u64 v[212:213], v[214:215], 0, s[92:93]
	s_add_i32 m0, s37, 0x2000
	s_nop 0
	global_load_lds_dwordx4 v[212:213], off
	s_barrier
	s_waitcnt lgkmcnt(0)
	s_setprio 1
	s_waitcnt lgkmcnt(0)
	v_mfma_f32_16x16x32_bf16 v[114:117], v[192:195], v[160:163], v[114:117]
	v_mfma_f32_16x16x32_bf16 v[106:109], v[204:207], v[160:163], v[106:109]
	v_mfma_f32_16x16x32_bf16 v[98:101], v[192:195], v[168:171], v[98:101]
	v_mfma_f32_16x16x32_bf16 v[90:93], v[204:207], v[168:171], v[90:93]
	v_mfma_f32_16x16x32_bf16 v[82:85], v[192:195], v[176:179], v[82:85]
	v_mfma_f32_16x16x32_bf16 v[74:77], v[204:207], v[176:179], v[74:77]
	v_mfma_f32_16x16x32_bf16 v[70:73], v[192:195], v[184:187], v[70:73]
	v_mfma_f32_16x16x32_bf16 v[66:69], v[204:207], v[184:187], v[66:69]
	v_mfma_f32_16x16x32_bf16 v[114:117], v[200:203], v[164:167], v[114:117]
	v_mfma_f32_16x16x32_bf16 v[106:109], v[208:211], v[164:167], v[106:109]
	v_mfma_f32_16x16x32_bf16 v[98:101], v[200:203], v[172:175], v[98:101]
	v_mfma_f32_16x16x32_bf16 v[90:93], v[208:211], v[172:175], v[90:93]
	v_mfma_f32_16x16x32_bf16 v[82:85], v[200:203], v[180:183], v[82:85]
	v_mfma_f32_16x16x32_bf16 v[74:77], v[208:211], v[180:183], v[74:77]
	v_mfma_f32_16x16x32_bf16 v[70:73], v[200:203], v[188:191], v[70:73]
	v_mfma_f32_16x16x32_bf16 v[66:69], v[208:211], v[188:191], v[66:69]
	s_setprio 0
	s_mov_b32 m0, s51
	v_lshl_add_u64 v[212:213], v[216:217], 0, s[92:93]
	s_barrier
	ds_read_b128 v[160:163], v147 offset:49152
	ds_read_b128 v[164:167], v147 offset:50176
	ds_read_b128 v[168:171], v147 offset:51200
	ds_read_b128 v[172:175], v147 offset:52224
	ds_read_b128 v[176:179], v147 offset:53248
	ds_read_b128 v[180:183], v147 offset:54272
	ds_read_b128 v[184:187], v147 offset:55296
	ds_read_b128 v[188:191], v147 offset:56320
	global_load_lds_dwordx4 v[212:213], off
	v_lshl_add_u64 v[212:213], v[218:219], 0, s[92:93]
	s_mov_b32 m0, s52
	s_nop 0
	global_load_lds_dwordx4 v[212:213], off
	s_barrier
; #define PG8_STAGE(bufoff, gbase, voff) do { _Pragma("unroll") for (int _i = 0; _i < 2; ++_i) \
;         __builtin_amdgcn_global_load_lds((const unsigned*)((const char*)(gbase) + (voff)[_i]), (LAS unsigned*)(lds + (bufoff) + ldsw + _i * 8192), 16, 0, 0); } while (0)
; #define PG8_MMA(ai, bj, At, Bt) do { __builtin_amdgcn_s_setprio(1); _Pragma("unroll") for (int m = 0; m < 4; ++m) _Pragma("unroll") for (int n = 0; n < 2; ++n) _Pragma("unroll") for (int k = 0; k < 2; ++k) \
;         acc[ai][bj][m][n] = __builtin_amdgcn_mfma_f32_16x16x32_bf16(Bt[n][k], At[m][k], acc[ai][bj][m][n], 0, 0, 0); __builtin_amdgcn_s_setprio(0); } while (0)
; #define PG8_WAIT_V(n) asm volatile("s_waitcnt vmcnt(" #n ")" ::: "memory")
; #define PG8_WAIT_L(n) asm volatile("s_waitcnt lgkmcnt(" #n ")" ::: "memory")
; #define PG8_BAR __builtin_amdgcn_s_barrier()
; #define PG8_SCHED __builtin_amdgcn_sched_barrier(0)
; template <class Epi>
; DEVI void gemm_phase(const int wv, LAS unsigned char* lds, const Gemm g, const Order& S, const Epi& E) {
;     ...
;             PG8_BAR; PG8_WAIT_L(0); PG8_MMA(1, 0, At, B0); PG8_BAR; PG8_SCHED;
;             PG8_STAGE(PG8_SB(1, 1), b3 + hstepB, voffB);
;             PG8_WAIT_V(6); PG8_BAR; PG8_MMA(1, 1, At, B1); PG8_BAR;
;         }
	s_waitcnt lgkmcnt(0)
	s_setprio 1
	s_waitcnt lgkmcnt(0)
	v_mfma_f32_16x16x32_bf16 v[62:65], v[140:143], v[160:163], v[62:65]
	v_mfma_f32_16x16x32_bf16 v[58:61], v[152:155], v[160:163], v[58:61]
	v_mfma_f32_16x16x32_bf16 v[54:57], v[140:143], v[168:171], v[54:57]
	v_mfma_f32_16x16x32_bf16 v[46:49], v[152:155], v[168:171], v[46:49]
	v_mfma_f32_16x16x32_bf16 v[38:41], v[140:143], v[176:179], v[38:41]
	v_mfma_f32_16x16x32_bf16 v[30:33], v[152:155], v[176:179], v[30:33]
	v_mfma_f32_16x16x32_bf16 v[22:25], v[140:143], v[184:187], v[22:25]
	v_mfma_f32_16x16x32_bf16 v[14:17], v[152:155], v[184:187], v[14:17]
	v_mfma_f32_16x16x32_bf16 v[62:65], v[148:151], v[164:167], v[62:65]
	v_mfma_f32_16x16x32_bf16 v[58:61], v[156:159], v[164:167], v[58:61]
	v_mfma_f32_16x16x32_bf16 v[54:57], v[148:151], v[172:175], v[54:57]
	v_mfma_f32_16x16x32_bf16 v[46:49], v[156:159], v[172:175], v[46:49]
	v_mfma_f32_16x16x32_bf16 v[38:41], v[148:151], v[180:183], v[38:41]
	v_mfma_f32_16x16x32_bf16 v[30:33], v[156:159], v[180:183], v[30:33]
	v_mfma_f32_16x16x32_bf16 v[22:25], v[148:151], v[188:191], v[22:25]
	v_mfma_f32_16x16x32_bf16 v[14:17], v[156:159], v[188:191], v[14:17]
	s_setprio 0
	s_barrier
	s_add_u32 s30, s30, 0x40080
	s_addc_u32 s31, s31, 0
	s_add_i32 s36, s36, s95
	v_lshl_add_u64 v[140:141], s[30:31], 0, v[0:1]
	s_mov_b32 m0, s36
	s_nop 0
	global_load_lds_dwordx4 v[140:141], off
	v_lshl_add_u64 v[140:141], s[30:31], 0, v[134:135]
	s_add_i32 m0, s36, 0x2000
	s_nop 0
	global_load_lds_dwordx4 v[140:141], off
	s_waitcnt vmcnt(6)
	s_barrier
	s_setprio 1
	v_mfma_f32_16x16x32_bf16 v[50:53], v[192:195], v[160:163], v[50:53]
	v_mfma_f32_16x16x32_bf16 v[42:45], v[204:207], v[160:163], v[42:45]
	v_mfma_f32_16x16x32_bf16 v[34:37], v[192:195], v[168:171], v[34:37]
	v_mfma_f32_16x16x32_bf16 v[26:29], v[204:207], v[168:171], v[26:29]
	v_mfma_f32_16x16x32_bf16 v[18:21], v[192:195], v[176:179], v[18:21]
	v_mfma_f32_16x16x32_bf16 v[10:13], v[204:207], v[176:179], v[10:13]
	v_mfma_f32_16x16x32_bf16 v[6:9], v[192:195], v[184:187], v[6:9]
	v_mfma_f32_16x16x32_bf16 v[2:5], v[204:207], v[184:187], v[2:5]
	v_mfma_f32_16x16x32_bf16 v[50:53], v[200:203], v[164:167], v[50:53]
	v_mfma_f32_16x16x32_bf16 v[42:45], v[208:211], v[164:167], v[42:45]
	v_mfma_f32_16x16x32_bf16 v[34:37], v[200:203], v[172:175], v[34:37]
	v_mfma_f32_16x16x32_bf16 v[26:29], v[208:211], v[172:175], v[26:29]
	v_mfma_f32_16x16x32_bf16 v[18:21], v[200:203], v[180:183], v[18:21]
	v_mfma_f32_16x16x32_bf16 v[10:13], v[208:211], v[180:183], v[10:13]
	v_mfma_f32_16x16x32_bf16 v[6:9], v[200:203], v[188:191], v[6:9]
	v_mfma_f32_16x16x32_bf16 v[2:5], v[208:211], v[188:191], v[2:5]
	s_setprio 0
	s_add_i32 s60, s60, 2
	s_add_u32 s28, s28, 0x100
	s_addc_u32 s29, s29, 0
	s_add_u32 s58, s58, 0x100
	s_addc_u32 s59, s59, 0
	s_cmp_gt_u32 s60, 13
	s_barrier
	s_cbranch_scc0 .LBB0_287
; DEVI unsigned cvt_pk_bf16(float lo, float hi) { unsigned r; asm volatile("v_cvt_pk_bf16_f32 %0, %1, %2" : "=v"(r) : "v"(lo), "v"(hi)); return r; }
; #define PG8_WAIT_V(n) asm volatile("s_waitcnt vmcnt(" #n ")" ::: "memory")
; #define PG8_BAR __builtin_amdgcn_s_barrier()
;     DEVI void operator()(f32x4 (&acc)[2][2][4][2], const Unit& u, int wr, int wc, int fr, int fq) const {
;     ...
;             for (int m = 0; m < 4; ++m) { bf16_t* rowp = O + (size_t)(row0 + ai * HALF + m * 16) * ldc + col0;
;                 float rstd = 1.0f; if (RS) rstd = rsqrtf(ssq[row0 + ai * HALF + m * 16] * (1.0f / 1024.0f) + EPS);
; #pragma unroll
;                 for (int bj = 0; bj < 2; ++bj) { f32x4 v0 = acc[ai][bj][m][0], v1 = acc[ai][bj][m][1];
;                     if (RS) { v0 = v0 * rstd + sh[bj][0]; v1 = v1 * rstd + sh[bj][1]; }
;                     if (ACT == 1) {
; #pragma unroll
;                         for (int j = 0; j < 4; ++j) { const float a = fmaxf(v0[j], 0.f), b = fmaxf(v1[j], 0.f); v0[j] = a * a; v1[j] = b * b; } }
;                     if (ACT == 2) {
; #pragma unroll
;                         for (int j = 0; j < 4; ++j) { v0[j] = 1.0f + __expf(-fminf(fmaxf(v0[j], -30.f), 30.f)); v1[j] = 1.0f + __expf(-fminf(fmaxf(v1[j], -30.f), 30.f)); } }
;                     u32x4 w; w.x = cvt_pk_bf16(v0[0], v0[1]); w.y = cvt_pk_bf16(v0[2], v0[3]); w.z = cvt_pk_bf16(v1[0], v1[1]); w.w = cvt_pk_bf16(v1[2], v1[3]);
;                     *(u32x4*)(rowp + bj * HALF) = w; } }
; template <class Epi>
; DEVI void gemm_phase(const int wv, LAS unsigned char* lds, const Gemm g, const Order& S, const Epi& E) {
;     ...
;         if (!has_next) break;
;         cur = nxt; cA = nA; cB = nB; ++ui;
;     }
;     PG8_WAIT_V(0);
;     if (wr == 0) PG8_BAR;
;     PG8_BAR;
	v_lshl_or_b32 v142, s0, 8, v146
	v_lshl_add_u32 v150, s2, 8, v144
	v_ashrrev_i32_e32 v143, 31, v142
	v_mov_b64_e32 v[140:141], s[24:25]
	v_mad_i64_i32 v[148:149], s[28:29], v150, s46, v[140:141]
	v_lshlrev_b64 v[142:143], 1, v[142:143]
	v_lshl_add_u64 v[148:149], v[148:149], 0, v[142:143]
	v_cvt_pk_bf16_f32 v126, v126, v127
	v_cvt_pk_bf16_f32 v127, v128, v129
	v_cvt_pk_bf16_f32 v128, v122, v123
	v_cvt_pk_bf16_f32 v129, v124, v125
	global_store_dwordx4 v[148:149], v[126:129], off
	v_cvt_pk_bf16_f32 v114, v114, v115
	v_cvt_pk_bf16_f32 v115, v116, v117
	v_cvt_pk_bf16_f32 v116, v106, v107
	v_or_b32_e32 v106, 16, v150
	v_mad_i64_i32 v[106:107], s[28:29], v106, s46, v[140:141]
	v_cvt_pk_bf16_f32 v117, v108, v109
	global_store_dwordx4 v[148:149], v[114:117], off offset:256
	s_and_b64 vcc, exec, s[10:11]
	s_mov_b32 s0, s4
	v_lshl_add_u64 v[114:115], v[106:107], 0, v[142:143]
	v_cvt_pk_bf16_f32 v106, v118, v119
	v_cvt_pk_bf16_f32 v107, v120, v121
	v_cvt_pk_bf16_f32 v108, v110, v111
	v_cvt_pk_bf16_f32 v109, v112, v113
	global_store_dwordx4 v[114:115], v[106:109], off
	v_cvt_pk_bf16_f32 v98, v98, v99
	v_cvt_pk_bf16_f32 v99, v100, v101
	v_cvt_pk_bf16_f32 v100, v90, v91
	v_or_b32_e32 v90, 32, v150
	v_mad_i64_i32 v[90:91], s[28:29], v90, s46, v[140:141]
	v_cvt_pk_bf16_f32 v101, v92, v93
	global_store_dwordx4 v[114:115], v[98:101], off offset:256
	s_mov_b32 s2, s6
	s_mov_b64 s[30:31], s[12:13]
	v_lshl_add_u64 v[98:99], v[90:91], 0, v[142:143]
	v_cvt_pk_bf16_f32 v90, v102, v103
	v_cvt_pk_bf16_f32 v91, v104, v105
	v_cvt_pk_bf16_f32 v92, v94, v95
	v_cvt_pk_bf16_f32 v93, v96, v97
	global_store_dwordx4 v[98:99], v[90:93], off
	v_cvt_pk_bf16_f32 v82, v82, v83
	v_cvt_pk_bf16_f32 v83, v84, v85
	v_cvt_pk_bf16_f32 v84, v74, v75
	v_or_b32_e32 v74, 48, v150
	v_mad_i64_i32 v[74:75], s[28:29], v74, s46, v[140:141]
	v_cvt_pk_bf16_f32 v85, v76, v77
	global_store_dwordx4 v[98:99], v[82:85], off offset:256
	s_nop 1
	v_lshl_add_u64 v[82:83], v[74:75], 0, v[142:143]
	v_cvt_pk_bf16_f32 v74, v86, v87
	v_cvt_pk_bf16_f32 v75, v88, v89
	v_cvt_pk_bf16_f32 v76, v78, v79
	v_cvt_pk_bf16_f32 v77, v80, v81
	global_store_dwordx4 v[82:83], v[74:77], off
	v_cvt_pk_bf16_f32 v70, v70, v71
	v_cvt_pk_bf16_f32 v71, v72, v73
	v_cvt_pk_bf16_f32 v72, v66, v67
	v_add_u32_e32 v66, 0x80, v150
	v_mad_i64_i32 v[66:67], s[28:29], v66, s46, v[140:141]
	v_lshl_add_u64 v[66:67], v[66:67], 0, v[142:143]
	v_cvt_pk_bf16_f32 v73, v68, v69
	global_store_dwordx4 v[82:83], v[70:73], off offset:256
	v_cvt_pk_bf16_f32 v62, v62, v63
	v_cvt_pk_bf16_f32 v63, v64, v65
	v_cvt_pk_bf16_f32 v64, v58, v59
	v_cvt_pk_bf16_f32 v65, v60, v61
	global_store_dwordx4 v[66:67], v[62:65], off
	v_cvt_pk_bf16_f32 v50, v50, v51
	v_cvt_pk_bf16_f32 v51, v52, v53
	v_cvt_pk_bf16_f32 v52, v42, v43
	v_add_u32_e32 v42, 0x90, v150
	v_mad_i64_i32 v[42:43], s[28:29], v42, s46, v[140:141]
	v_cvt_pk_bf16_f32 v53, v44, v45
	global_store_dwordx4 v[66:67], v[50:53], off offset:256
	s_nop 1
	v_lshl_add_u64 v[50:51], v[42:43], 0, v[142:143]
	v_cvt_pk_bf16_f32 v42, v54, v55
	v_cvt_pk_bf16_f32 v43, v56, v57
	v_cvt_pk_bf16_f32 v44, v46, v47
	v_cvt_pk_bf16_f32 v45, v48, v49
	global_store_dwordx4 v[50:51], v[42:45], off
	v_cvt_pk_bf16_f32 v34, v34, v35
	v_cvt_pk_bf16_f32 v35, v36, v37
	v_cvt_pk_bf16_f32 v36, v26, v27
	v_add_u32_e32 v26, 0xa0, v150
	v_mad_i64_i32 v[26:27], s[28:29], v26, s46, v[140:141]
	v_cvt_pk_bf16_f32 v37, v28, v29
	global_store_dwordx4 v[50:51], v[34:37], off offset:256
	s_nop 1
	v_lshl_add_u64 v[34:35], v[26:27], 0, v[142:143]
	v_cvt_pk_bf16_f32 v26, v38, v39
	v_cvt_pk_bf16_f32 v27, v40, v41
	v_cvt_pk_bf16_f32 v28, v30, v31
	v_cvt_pk_bf16_f32 v29, v32, v33
	global_store_dwordx4 v[34:35], v[26:29], off
	v_cvt_pk_bf16_f32 v18, v18, v19
	v_cvt_pk_bf16_f32 v19, v20, v21
	v_cvt_pk_bf16_f32 v20, v10, v11
	v_add_u32_e32 v10, 0xb0, v150
	v_mad_i64_i32 v[10:11], s[28:29], v10, s46, v[140:141]
	v_cvt_pk_bf16_f32 v21, v12, v13
	global_store_dwordx4 v[34:35], v[18:21], off offset:256
	s_mov_b64 s[28:29], s[8:9]
	s_nop 0
	v_lshl_add_u64 v[18:19], v[10:11], 0, v[142:143]
	v_cvt_pk_bf16_f32 v10, v22, v23
	v_cvt_pk_bf16_f32 v11, v24, v25
	v_cvt_pk_bf16_f32 v12, v14, v15
	v_cvt_pk_bf16_f32 v13, v16, v17
	global_store_dwordx4 v[18:19], v[10:13], off
	v_cvt_pk_bf16_f32 v6, v6, v7
	v_cvt_pk_bf16_f32 v7, v8, v9
	v_cvt_pk_bf16_f32 v8, v2, v3
	v_cvt_pk_bf16_f32 v9, v4, v5
	global_store_dwordx4 v[18:19], v[6:9], off offset:256
	s_cbranch_vccz .LBB0_281
	v_readlane_b32 s0, v252, 13
	s_waitcnt vmcnt(0)
	v_readlane_b32 s1, v252, 14
	s_andn2_b64 vcc, exec, s[0:1]
	s_movk_i32 s55, 0xc00
	s_cbranch_vccnz .LBB0_291
	s_barrier

; DEVI int opaque_tid(int wv) { int ln; asm volatile("v_mbcnt_lo_u32_b32 %0, -1, 0\n\tv_mbcnt_hi_u32_b32 %0, -1, %0" : "=v"(ln)); return wv * 64 + ln; }
;     DEVI bool next(int i, Unit& u) const {
;         const int ti = i / nb; u.pb = i - ti * nb;
;         const long L = (long)ti * G + c;
;         if (L >= nwg) { const int t = (int)(L - nwg); if (t >= tail_units) return false; u.pm = nM + t / tail_nN; u.pn = t % tail_nN; return true; }
; template <class Epi>
; DEVI void gemm_phase(const int wv, LAS unsigned char* lds, const Gemm g, const Order& S, const Epi& E) {
;     const int tid = opaque_tid(wv), wid = wv, lane = tid & 63, wr = wid >> 2, wc = wid & 3, fr = lane & 15, fq = lane >> 4;
;     const int K = g.K, nt = K / BK;
;     unsigned voffA[2], voffB[2];
; #pragma unroll
;     for (int i = 0; i < 2; ++i) { int R, C; stage_rc(tid * 16 + i * 8192, R, C); const int Rb = Epi::PERM ? ((R & ~31) + perm32(R & 31)) : R;
;         voffA[i] = (unsigned)(R * g.lda + C) * 2u; voffB[i] = (unsigned)(Rb * g.ldb + C) * 2u; }
;     const size_t kstep = (size_t)(BK * 2);
;     const size_t hstepA = (size_t)HALF * g.lda * 2, hstepB = (size_t)HALF * g.ldb * 2;
;     const size_t tstepA = 2 * hstepA, tstepB = 2 * hstepB;
;     const unsigned ldsw = (unsigned)wid * 1024u;
;     const int aoff = lds_byte(wr * 64 + fr, fq * 8), boff = lds_byte(wc * 32 + fr, fq * 8);
;     ...
;     Unit cur, nxt; int ui = 0;
;     if (!S.next(0, cur)) return;
;     f32x4 acc[2][2][4][2];
; #pragma unroll
;     for (int a = 0; a < 2; ++a)
; #pragma unroll
;         for (int b = 0; b < 2; ++b)
; #pragma unroll
;             for (int m = 0; m < 4; ++m)
; #pragma unroll
;                 for (int n = 0; n < 2; ++n) acc[a][b][m][n] = (f32x4){0.f, 0.f, 0.f, 0.f};
;     bf16x8 At[4][2], B0[2][2], B1[2][2];
;     const char* cA = (const char*)g.A + (size_t)cur.pb * g.a_bs + (size_t)cur.pm * tstepA; const char* cB = (const char*)g.Bt + (size_t)cur.pb * g.b_bs + (size_t)cur.pn * tstepB;
;     PG8_STAGE(PG8_SB(0, 0), cB, voffB); PG8_STAGE(PG8_SA(0, 0), cA, voffA); PG8_STAGE(PG8_SB(0, 1), cB + hstepB, voffB); PG8_STAGE(PG8_SA(0, 1), cA + hstepA, voffA);
;     if (wr == 1) PG8_BAR;
;     PG8_WAIT_V(4); PG8_BAR;
;     PG8_STAGE(PG8_SB(1, 0), cB + kstep, voffB); PG8_STAGE(PG8_SA(1, 0), cA + kstep, voffA); PG8_STAGE(PG8_SB(1, 1), cB + hstepB + kstep, voffB);
;     PG8_WAIT_V(6); PG8_BAR;
.LBB0_808:
	v_and_b32_e32 v9, 15, v8
	v_readlane_b32 s0, v252, 6
	v_lshrrev_b32_e32 v18, 1, v8
	v_and_b32_e32 v18, 24, v18
	v_or_b32_e32 v144, s0, v9
	v_lshlrev_b32_e32 v19, 6, v144
	v_lshlrev_b32_e32 v20, 1, v18
	s_movk_i32 s0, 0x3c0
	v_lshlrev_b32_e32 v21, 2, v144
	v_and_or_b32 v19, v19, s0, v20
	v_and_b32_e32 v21, 32, v21
	v_readlane_b32 s0, v252, 7
	v_lshlrev_b32_e32 v8, 2, v8
	v_lshl_add_u64 v[10:11], s[30:31], 0, v[0:1]
	v_mov_b32_e32 v131, v1
	v_bitop3_b32 v19, v19, s0, v21 bitop3:0xde
	v_lshl_or_b32 v9, v9, 6, v20
	v_and_b32_e32 v8, 32, v8
	v_readlane_b32 s0, v252, 9
	v_lshl_add_u64 v[12:13], s[30:31], 0, v[130:131]
	v_mov_b32_e32 v135, v1
	v_bitop3_b32 v145, v9, s0, v8 bitop3:0xde
	v_lshl_add_u64 v[8:9], v[10:11], 0, s[92:93]
	s_add_i32 m0, s11, 0x18000
	v_lshl_add_u64 v[14:15], s[28:29], 0, v[134:135]
	v_mov_b32_e32 v133, v1
	s_waitcnt vmcnt(4)
	s_barrier
	global_load_lds_dwordx4 v[8:9], off
	v_lshl_add_u64 v[8:9], v[12:13], 0, s[92:93]
	s_add_i32 m0, s11, 0x1a000
	s_add_i32 s50, s11, 0x8000
	s_add_i32 s51, s11, 0xa000
	v_lshl_add_u64 v[16:17], s[28:29], 0, v[132:133]
	global_load_lds_dwordx4 v[8:9], off
	v_lshl_add_u64 v[8:9], v[14:15], 0, s[92:93]
	s_mov_b32 m0, s50
	s_add_u32 s0, s30, 0x40080
	global_load_lds_dwordx4 v[8:9], off
	v_lshl_add_u64 v[8:9], v[16:17], 0, s[92:93]
	s_mov_b32 m0, s51
	s_addc_u32 s1, s31, 0
	global_load_lds_dwordx4 v[8:9], off
	v_lshl_add_u64 v[8:9], s[0:1], 0, v[0:1]
	s_add_i32 m0, s11, 0x1c000
	v_mov_b32_e32 v137, v1
	global_load_lds_dwordx4 v[8:9], off
	v_lshl_add_u64 v[8:9], s[0:1], 0, v[130:131]
	s_add_i32 m0, s11, 0x1e000
	v_readlane_b32 s0, v252, 8
	global_load_lds_dwordx4 v[8:9], off
	v_lshlrev_b32_e32 v8, 14, v5
	v_and_b32_e32 v8, 0xffff8000, v8
	v_lshl_add_u32 v6, v6, 11, v8
	v_and_b32_e32 v5, 1, v5
	v_lshl_or_b32 v5, v5, 6, v6
	v_lshl_add_u32 v136, v7, 1, v5
	v_lshlrev_b32_e32 v5, 14, v2
	v_and_b32_e32 v5, 0xffff8000, v5
	s_waitcnt vmcnt(6)
	v_lshl_add_u32 v3, v3, 11, v5
	v_and_b32_e32 v2, 1, v2
	v_lshl_or_b32 v2, v2, 6, v3
	v_or_b32_e32 v146, s0, v18
	v_lshl_add_u32 v138, v4, 1, v2
	v_mov_b32_e32 v139, v1
	s_mov_b32 s52, 0
	v_add_u32_e32 v147, 0, v19
	s_barrier
.LBB0_809:
	s_add_i32 s52, s52, 1
	v_readlane_b32 s1, v252, 12
	s_mul_i32 s1, s52, s1
	s_mul_hi_u32 s3, s52, s33
	s_add_i32 s3, s3, s1
	s_mul_i32 s1, s52, s33
	v_readlane_b32 s4, v253, 12
	s_add_u32 s4, s1, s4
	v_readlane_b32 s1, v252, 4
	s_addc_u32 s5, s3, s1
	v_mov_b64_e32 v[2:3], s[18:19]
	v_cmp_lt_i64_e32 vcc, s[4:5], v[2:3]
	s_mov_b64 s[6:7], -1
	s_cbranch_vccnz .LBB0_811
	s_sub_i32 s1, s4, s18
	s_mov_b64 s[6:7], 0
	s_cmp_gt_i32 s1, -1
	s_mov_b64 s[36:37], 0
	s_cbranch_scc0 .LBB0_816

; #define PG8_STAGE(bufoff, gbase, voff) do { _Pragma("unroll") for (int _i = 0; _i < 2; ++_i) \
;         __builtin_amdgcn_global_load_lds((const unsigned*)((const char*)(gbase) + (voff)[_i]), (LAS unsigned*)(lds + (bufoff) + ldsw + _i * 8192), 16, 0, 0); } while (0)
; #define PG8_LDA(dst, b, h) do { _Pragma("unroll") for (int m = 0; m < 4; ++m) _Pragma("unroll") for (int k = 0; k < 2; ++k) dst[m][k] = *(const LAS bf16x8*)(lds + PG8_SA(b, h) + aoff + m * 2048 + k * 1024); } while (0)
; #define PG8_LDB(dst, b, h) do { _Pragma("unroll") for (int n = 0; n < 2; ++n) _Pragma("unroll") for (int k = 0; k < 2; ++k) dst[n][k] = *(const LAS bf16x8*)(lds + PG8_SB(b, h) + boff + n * 2048 + k * 1024); } while (0)
; #define PG8_MMA(ai, bj, At, Bt) do { __builtin_amdgcn_s_setprio(1); _Pragma("unroll") for (int m = 0; m < 4; ++m) _Pragma("unroll") for (int n = 0; n < 2; ++n) _Pragma("unroll") for (int k = 0; k < 2; ++k) \
;         acc[ai][bj][m][n] = __builtin_amdgcn_mfma_f32_16x16x32_bf16(Bt[n][k], At[m][k], acc[ai][bj][m][n], 0, 0, 0); __builtin_amdgcn_s_setprio(0); } while (0)
; #define PG8_WAIT_V(n) asm volatile("s_waitcnt vmcnt(" #n ")" ::: "memory")
; #define PG8_WAIT_L(n) asm volatile("s_waitcnt lgkmcnt(" #n ")" ::: "memory")
; #define PG8_BAR __builtin_amdgcn_s_barrier()
; #define PG8_SCHED __builtin_amdgcn_sched_barrier(0)
; template <class Epi>
; DEVI void gemm_phase(const int wv, LAS unsigned char* lds, const Gemm g, const Order& S, const Epi& E) {
;     ...
;             PG8_LDB(B0, 0, 0); PG8_SCHED; PG8_LDA(At, 0, 0); PG8_STAGE(PG8_SA(1, 1), a1 + hstepA, voffA);
;             PG8_WAIT_L(8); PG8_BAR; PG8_WAIT_L(0); PG8_MMA(0, 0, At, B0); PG8_BAR; PG8_SCHED;
;             PG8_LDB(B1, 0, 1); PG8_STAGE(PG8_SB(0, 0), b2, voffB);
;             PG8_BAR; PG8_WAIT_L(0); PG8_MMA(0, 1, At, B1); PG8_BAR;
;             PG8_LDA(At, 0, 1); PG8_STAGE(PG8_SA(0, 0), a2, voffA);
;             PG8_BAR; PG8_WAIT_L(0); PG8_MMA(1, 0, At, B0); PG8_BAR; PG8_SCHED;
;             PG8_STAGE(PG8_SB(0, 1), b2 + hstepB, voffB);
;             PG8_WAIT_V(6); PG8_BAR; PG8_MMA(1, 1, At, B1); PG8_BAR;
.LBB0_814:
	s_add_u32 s30, s28, 0xfffc0080
	s_addc_u32 s31, s29, -1
	s_add_i32 s58, 0, 0x10000
	v_add_u32_e32 v156, s58, v145
	ds_read_b128 v[140:143], v156
	ds_read_b128 v[148:151], v156 offset:1024
	ds_read_b128 v[152:155], v156 offset:2048
	ds_read_b128 v[156:159], v156 offset:3072
	s_cmp_eq_u32 s57, 12
	s_cselect_b32 s37, s3, s31
	s_cselect_b32 s36, s53, s30
	s_cselect_b32 s31, s1, s56
	s_cselect_b32 s30, s54, s55
	v_lshl_add_u64 v[192:193], s[28:29], 0, v[136:137]
	s_add_i32 m0, s11, 0xc000
	ds_read_b128 v[160:163], v147
	ds_read_b128 v[164:167], v147 offset:1024
	ds_read_b128 v[168:171], v147 offset:2048
	ds_read_b128 v[172:175], v147 offset:3072
	ds_read_b128 v[176:179], v147 offset:4096
	ds_read_b128 v[180:183], v147 offset:5120
	ds_read_b128 v[184:187], v147 offset:6144
	ds_read_b128 v[188:191], v147 offset:7168
	global_load_lds_dwordx4 v[192:193], off
	v_lshl_add_u64 v[192:193], s[28:29], 0, v[138:139]
	s_add_i32 m0, s11, 0xe000
	s_nop 0
	global_load_lds_dwordx4 v[192:193], off
	s_waitcnt lgkmcnt(8)
	s_barrier
	s_waitcnt lgkmcnt(0)
	s_setprio 1
	s_waitcnt lgkmcnt(0)
	v_mfma_f32_16x16x32_bf16 v[126:129], v[140:143], v[160:163], v[126:129]
	v_mfma_f32_16x16x32_bf16 v[122:125], v[152:155], v[160:163], v[122:125]
	v_mfma_f32_16x16x32_bf16 v[110:113], v[140:143], v[168:171], v[110:113]
	v_mfma_f32_16x16x32_bf16 v[106:109], v[152:155], v[168:171], v[106:109]
	v_mfma_f32_16x16x32_bf16 v[94:97], v[140:143], v[176:179], v[94:97]
	v_mfma_f32_16x16x32_bf16 v[90:93], v[152:155], v[176:179], v[90:93]
	v_mfma_f32_16x16x32_bf16 v[78:81], v[140:143], v[184:187], v[78:81]
	v_mfma_f32_16x16x32_bf16 v[74:77], v[152:155], v[184:187], v[74:77]
	v_mfma_f32_16x16x32_bf16 v[126:129], v[148:151], v[164:167], v[126:129]
	v_mfma_f32_16x16x32_bf16 v[122:125], v[156:159], v[164:167], v[122:125]
	v_mfma_f32_16x16x32_bf16 v[110:113], v[148:151], v[172:175], v[110:113]
	v_mfma_f32_16x16x32_bf16 v[106:109], v[156:159], v[172:175], v[106:109]
	v_mfma_f32_16x16x32_bf16 v[94:97], v[148:151], v[180:183], v[94:97]
	v_mfma_f32_16x16x32_bf16 v[90:93], v[156:159], v[180:183], v[90:93]
	v_mfma_f32_16x16x32_bf16 v[78:81], v[148:151], v[188:191], v[78:81]
	v_mfma_f32_16x16x32_bf16 v[74:77], v[156:159], v[188:191], v[74:77]
	s_setprio 0
	s_barrier
	s_add_i32 s60, 0, 0x14000
	s_add_i32 s58, s58, s95
	v_add_u32_e32 v199, s60, v145
	v_lshl_add_u64 v[212:213], s[30:31], 0, v[0:1]
	s_mov_b32 m0, s58
	ds_read_b128 v[192:195], v199
	ds_read_b128 v[200:203], v199 offset:1024
	ds_read_b128 v[204:207], v199 offset:2048
	ds_read_b128 v[208:211], v199 offset:3072
	global_load_lds_dwordx4 v[212:213], off
	v_lshl_add_u64 v[214:215], s[30:31], 0, v[130:131]
	s_add_i32 m0, s58, 0x2000
	s_nop 0
	global_load_lds_dwordx4 v[214:215], off
	s_barrier
	s_waitcnt lgkmcnt(0)
	s_setprio 1
	s_waitcnt lgkmcnt(0)
	v_mfma_f32_16x16x32_bf16 v[118:121], v[192:195], v[160:163], v[118:121]
	v_mfma_f32_16x16x32_bf16 v[114:117], v[204:207], v[160:163], v[114:117]
	v_mfma_f32_16x16x32_bf16 v[102:105], v[192:195], v[168:171], v[102:105]
	v_mfma_f32_16x16x32_bf16 v[98:101], v[204:207], v[168:171], v[98:101]
	v_mfma_f32_16x16x32_bf16 v[86:89], v[192:195], v[176:179], v[86:89]
	v_mfma_f32_16x16x32_bf16 v[82:85], v[204:207], v[176:179], v[82:85]
	v_mfma_f32_16x16x32_bf16 v[70:73], v[192:195], v[184:187], v[70:73]
	v_mfma_f32_16x16x32_bf16 v[66:69], v[204:207], v[184:187], v[66:69]
	v_mfma_f32_16x16x32_bf16 v[118:121], v[200:203], v[164:167], v[118:121]
	v_mfma_f32_16x16x32_bf16 v[114:117], v[208:211], v[164:167], v[114:117]
	v_mfma_f32_16x16x32_bf16 v[102:105], v[200:203], v[172:175], v[102:105]
	v_mfma_f32_16x16x32_bf16 v[98:101], v[208:211], v[172:175], v[98:101]
	v_mfma_f32_16x16x32_bf16 v[86:89], v[200:203], v[180:183], v[86:89]
	v_mfma_f32_16x16x32_bf16 v[82:85], v[208:211], v[180:183], v[82:85]
	v_mfma_f32_16x16x32_bf16 v[70:73], v[200:203], v[188:191], v[70:73]
	v_mfma_f32_16x16x32_bf16 v[66:69], v[208:211], v[188:191], v[66:69]
	s_setprio 0
	s_mov_b32 m0, s11
	v_lshl_add_u64 v[216:217], s[36:37], 0, v[134:135]
	s_barrier
	ds_read_b128 v[160:163], v147 offset:16384
	ds_read_b128 v[164:167], v147 offset:17408
	ds_read_b128 v[168:171], v147 offset:18432
	ds_read_b128 v[172:175], v147 offset:19456
	ds_read_b128 v[176:179], v147 offset:20480
	ds_read_b128 v[180:183], v147 offset:21504
	ds_read_b128 v[184:187], v147 offset:22528
	ds_read_b128 v[188:191], v147 offset:23552
	global_load_lds_dwordx4 v[216:217], off
	v_lshl_add_u64 v[218:219], s[36:37], 0, v[132:133]
	s_mov_b32 m0, s13
	s_nop 0
	global_load_lds_dwordx4 v[218:219], off
	s_barrier
	s_waitcnt lgkmcnt(0)
	s_setprio 1
	s_waitcnt lgkmcnt(0)
	v_mfma_f32_16x16x32_bf16 v[62:65], v[140:143], v[160:163], v[62:65]
	v_mfma_f32_16x16x32_bf16 v[58:61], v[152:155], v[160:163], v[58:61]
	v_mfma_f32_16x16x32_bf16 v[46:49], v[140:143], v[168:171], v[46:49]
	v_mfma_f32_16x16x32_bf16 v[42:45], v[152:155], v[168:171], v[42:45]
	v_mfma_f32_16x16x32_bf16 v[30:33], v[140:143], v[176:179], v[30:33]
	v_mfma_f32_16x16x32_bf16 v[26:29], v[152:155], v[176:179], v[26:29]
	v_mfma_f32_16x16x32_bf16 v[14:17], v[140:143], v[184:187], v[14:17]
	v_mfma_f32_16x16x32_bf16 v[10:13], v[152:155], v[184:187], v[10:13]
	v_mfma_f32_16x16x32_bf16 v[62:65], v[148:151], v[164:167], v[62:65]
	v_mfma_f32_16x16x32_bf16 v[58:61], v[156:159], v[164:167], v[58:61]
	v_mfma_f32_16x16x32_bf16 v[46:49], v[148:151], v[172:175], v[46:49]
	v_mfma_f32_16x16x32_bf16 v[42:45], v[156:159], v[172:175], v[42:45]
	v_mfma_f32_16x16x32_bf16 v[30:33], v[148:151], v[180:183], v[30:33]
	v_mfma_f32_16x16x32_bf16 v[26:29], v[156:159], v[180:183], v[26:29]
	v_mfma_f32_16x16x32_bf16 v[14:17], v[148:151], v[188:191], v[14:17]
	v_mfma_f32_16x16x32_bf16 v[10:13], v[156:159], v[188:191], v[10:13]
	s_setprio 0
	s_barrier
; #define PG8_STAGE(bufoff, gbase, voff) do { _Pragma("unroll") for (int _i = 0; _i < 2; ++_i) \
;         __builtin_amdgcn_global_load_lds((const unsigned*)((const char*)(gbase) + (voff)[_i]), (LAS unsigned*)(lds + (bufoff) + ldsw + _i * 8192), 16, 0, 0); } while (0)
; #define PG8_LDA(dst, b, h) do { _Pragma("unroll") for (int m = 0; m < 4; ++m) _Pragma("unroll") for (int k = 0; k < 2; ++k) dst[m][k] = *(const LAS bf16x8*)(lds + PG8_SA(b, h) + aoff + m * 2048 + k * 1024); } while (0)
; #define PG8_LDB(dst, b, h) do { _Pragma("unroll") for (int n = 0; n < 2; ++n) _Pragma("unroll") for (int k = 0; k < 2; ++k) dst[n][k] = *(const LAS bf16x8*)(lds + PG8_SB(b, h) + boff + n * 2048 + k * 1024); } while (0)
; #define PG8_MMA(ai, bj, At, Bt) do { __builtin_amdgcn_s_setprio(1); _Pragma("unroll") for (int m = 0; m < 4; ++m) _Pragma("unroll") for (int n = 0; n < 2; ++n) _Pragma("unroll") for (int k = 0; k < 2; ++k) \
;         acc[ai][bj][m][n] = __builtin_amdgcn_mfma_f32_16x16x32_bf16(Bt[n][k], At[m][k], acc[ai][bj][m][n], 0, 0, 0); __builtin_amdgcn_s_setprio(0); } while (0)
; #define PG8_WAIT_V(n) asm volatile("s_waitcnt vmcnt(" #n ")" ::: "memory")
; #define PG8_WAIT_L(n) asm volatile("s_waitcnt lgkmcnt(" #n ")" ::: "memory")
; #define PG8_BAR __builtin_amdgcn_s_barrier()
; #define PG8_SCHED __builtin_amdgcn_sched_barrier(0)
; template <class Epi>
; DEVI void gemm_phase(const int wv, LAS unsigned char* lds, const Gemm g, const Order& S, const Epi& E) {
;     ...
;             PG8_STAGE(PG8_SB(0, 1), b2 + hstepB, voffB);
;             PG8_WAIT_V(6); PG8_BAR; PG8_MMA(1, 1, At, B1); PG8_BAR;
;             PG8_LDB(B0, 1, 0); PG8_SCHED; PG8_LDA(At, 1, 0); PG8_STAGE(PG8_SA(0, 1), a2 + hstepA, voffA);
;             PG8_WAIT_L(8); PG8_BAR; PG8_WAIT_L(0); PG8_MMA(0, 0, At, B0); PG8_BAR; PG8_SCHED;
;             PG8_LDB(B1, 1, 1); PG8_STAGE(PG8_SB(1, 0), b3, voffB);
;             PG8_BAR; PG8_WAIT_L(0); PG8_MMA(0, 1, At, B1); PG8_BAR;
;             PG8_LDA(At, 1, 1); PG8_STAGE(PG8_SA(1, 0), a3, voffA);
	s_add_u32 s58, s30, 0x40000
	s_addc_u32 s59, s31, 0
	s_add_i32 s60, s60, s95
	v_lshl_add_u64 v[140:141], s[58:59], 0, v[0:1]
	s_mov_b32 m0, s60
	s_nop 0
	global_load_lds_dwordx4 v[140:141], off
	v_lshl_add_u64 v[140:141], s[58:59], 0, v[130:131]
	s_add_i32 m0, s60, 0x2000
	s_nop 0
	global_load_lds_dwordx4 v[140:141], off
	s_waitcnt vmcnt(6)
	s_barrier
	s_setprio 1
	v_mfma_f32_16x16x32_bf16 v[54:57], v[192:195], v[160:163], v[54:57]
	v_mfma_f32_16x16x32_bf16 v[50:53], v[204:207], v[160:163], v[50:53]
	v_mfma_f32_16x16x32_bf16 v[38:41], v[192:195], v[168:171], v[38:41]
	v_mfma_f32_16x16x32_bf16 v[34:37], v[204:207], v[168:171], v[34:37]
	v_mfma_f32_16x16x32_bf16 v[22:25], v[192:195], v[176:179], v[22:25]
	v_mfma_f32_16x16x32_bf16 v[18:21], v[204:207], v[176:179], v[18:21]
	v_mfma_f32_16x16x32_bf16 v[6:9], v[192:195], v[184:187], v[6:9]
	v_mfma_f32_16x16x32_bf16 v[2:5], v[204:207], v[184:187], v[2:5]
	v_mfma_f32_16x16x32_bf16 v[54:57], v[200:203], v[164:167], v[54:57]
	v_mfma_f32_16x16x32_bf16 v[50:53], v[208:211], v[164:167], v[50:53]
	v_mfma_f32_16x16x32_bf16 v[38:41], v[200:203], v[172:175], v[38:41]
	v_mfma_f32_16x16x32_bf16 v[34:37], v[208:211], v[172:175], v[34:37]
	v_mfma_f32_16x16x32_bf16 v[22:25], v[200:203], v[180:183], v[22:25]
	v_mfma_f32_16x16x32_bf16 v[18:21], v[208:211], v[180:183], v[18:21]
	v_mfma_f32_16x16x32_bf16 v[6:9], v[200:203], v[188:191], v[6:9]
	v_mfma_f32_16x16x32_bf16 v[2:5], v[208:211], v[188:191], v[2:5]
	s_setprio 0
	s_add_i32 s58, 0, 0x18000
	v_add_u32_e32 v156, s58, v145
	s_barrier
	ds_read_b128 v[140:143], v156
	ds_read_b128 v[148:151], v156 offset:1024
	ds_read_b128 v[152:155], v156 offset:2048
	ds_read_b128 v[156:159], v156 offset:3072
	s_add_u32 s36, s36, 0x40000
	s_addc_u32 s37, s37, 0
	s_mov_b32 m0, s40
	v_lshl_add_u64 v[192:193], s[36:37], 0, v[134:135]
	ds_read_b128 v[160:163], v147 offset:32768
	ds_read_b128 v[164:167], v147 offset:33792
	ds_read_b128 v[168:171], v147 offset:34816
	ds_read_b128 v[172:175], v147 offset:35840
	ds_read_b128 v[176:179], v147 offset:36864
	ds_read_b128 v[180:183], v147 offset:37888
	ds_read_b128 v[184:187], v147 offset:38912
	ds_read_b128 v[188:191], v147 offset:39936
	global_load_lds_dwordx4 v[192:193], off
	v_lshl_add_u64 v[192:193], s[36:37], 0, v[132:133]
	s_mov_b32 m0, s41
	s_nop 0
	global_load_lds_dwordx4 v[192:193], off
	s_waitcnt lgkmcnt(8)
	s_barrier
	s_waitcnt lgkmcnt(0)
	s_setprio 1
	s_waitcnt lgkmcnt(0)
	v_mfma_f32_16x16x32_bf16 v[126:129], v[140:143], v[160:163], v[126:129]
	v_mfma_f32_16x16x32_bf16 v[122:125], v[152:155], v[160:163], v[122:125]
	v_mfma_f32_16x16x32_bf16 v[110:113], v[140:143], v[168:171], v[110:113]
	v_mfma_f32_16x16x32_bf16 v[106:109], v[152:155], v[168:171], v[106:109]
	v_mfma_f32_16x16x32_bf16 v[94:97], v[140:143], v[176:179], v[94:97]
	v_mfma_f32_16x16x32_bf16 v[90:93], v[152:155], v[176:179], v[90:93]
	v_mfma_f32_16x16x32_bf16 v[78:81], v[140:143], v[184:187], v[78:81]
	v_mfma_f32_16x16x32_bf16 v[74:77], v[152:155], v[184:187], v[74:77]
	v_mfma_f32_16x16x32_bf16 v[126:129], v[148:151], v[164:167], v[126:129]
	v_mfma_f32_16x16x32_bf16 v[122:125], v[156:159], v[164:167], v[122:125]
	v_mfma_f32_16x16x32_bf16 v[110:113], v[148:151], v[172:175], v[110:113]
	v_mfma_f32_16x16x32_bf16 v[106:109], v[156:159], v[172:175], v[106:109]
	v_mfma_f32_16x16x32_bf16 v[94:97], v[148:151], v[180:183], v[94:97]
	v_mfma_f32_16x16x32_bf16 v[90:93], v[156:159], v[180:183], v[90:93]
	v_mfma_f32_16x16x32_bf16 v[78:81], v[148:151], v[188:191], v[78:81]
	v_mfma_f32_16x16x32_bf16 v[74:77], v[156:159], v[188:191], v[74:77]
	s_setprio 0
	s_barrier
	s_add_i32 s36, 0, 0x1c000
	s_add_i32 s37, s58, s95
	v_add_u32_e32 v199, s36, v145
	v_lshl_add_u64 v[212:213], v[212:213], 0, s[92:93]
	s_mov_b32 m0, s37
	ds_read_b128 v[192:195], v199
	ds_read_b128 v[200:203], v199 offset:1024
	ds_read_b128 v[204:207], v199 offset:2048
	ds_read_b128 v[208:211], v199 offset:3072
	global_load_lds_dwordx4 v[212:213], off
	v_lshl_add_u64 v[212:213], v[214:215], 0, s[92:93]
	s_add_i32 m0, s37, 0x2000
	s_nop 0
	global_load_lds_dwordx4 v[212:213], off
	s_barrier
	s_waitcnt lgkmcnt(0)
	s_setprio 1
	s_waitcnt lgkmcnt(0)
	v_mfma_f32_16x16x32_bf16 v[118:121], v[192:195], v[160:163], v[118:121]
	v_mfma_f32_16x16x32_bf16 v[114:117], v[204:207], v[160:163], v[114:117]
	v_mfma_f32_16x16x32_bf16 v[102:105], v[192:195], v[168:171], v[102:105]
	v_mfma_f32_16x16x32_bf16 v[98:101], v[204:207], v[168:171], v[98:101]
	v_mfma_f32_16x16x32_bf16 v[86:89], v[192:195], v[176:179], v[86:89]
	v_mfma_f32_16x16x32_bf16 v[82:85], v[204:207], v[176:179], v[82:85]
	v_mfma_f32_16x16x32_bf16 v[70:73], v[192:195], v[184:187], v[70:73]
	v_mfma_f32_16x16x32_bf16 v[66:69], v[204:207], v[184:187], v[66:69]
	v_mfma_f32_16x16x32_bf16 v[118:121], v[200:203], v[164:167], v[118:121]
	v_mfma_f32_16x16x32_bf16 v[114:117], v[208:211], v[164:167], v[114:117]
	v_mfma_f32_16x16x32_bf16 v[102:105], v[200:203], v[172:175], v[102:105]
	v_mfma_f32_16x16x32_bf16 v[98:101], v[208:211], v[172:175], v[98:101]
	v_mfma_f32_16x16x32_bf16 v[86:89], v[200:203], v[180:183], v[86:89]
	v_mfma_f32_16x16x32_bf16 v[82:85], v[208:211], v[180:183], v[82:85]
	v_mfma_f32_16x16x32_bf16 v[70:73], v[200:203], v[188:191], v[70:73]
	v_mfma_f32_16x16x32_bf16 v[66:69], v[208:211], v[188:191], v[66:69]
	s_setprio 0
	s_mov_b32 m0, s50
	v_lshl_add_u64 v[212:213], v[216:217], 0, s[92:93]
	s_barrier
	ds_read_b128 v[160:163], v147 offset:49152
	ds_read_b128 v[164:167], v147 offset:50176
	ds_read_b128 v[168:171], v147 offset:51200
	ds_read_b128 v[172:175], v147 offset:52224
	ds_read_b128 v[176:179], v147 offset:53248
	ds_read_b128 v[180:183], v147 offset:54272
	ds_read_b128 v[184:187], v147 offset:55296
	ds_read_b128 v[188:191], v147 offset:56320
	global_load_lds_dwordx4 v[212:213], off
	v_lshl_add_u64 v[212:213], v[218:219], 0, s[92:93]
	s_mov_b32 m0, s51
	s_nop 0
	global_load_lds_dwordx4 v[212:213], off
	s_barrier
; DEVI unsigned cvt_pk_bf16(float lo, float hi) { unsigned r; asm volatile("v_cvt_pk_bf16_f32 %0, %1, %2" : "=v"(r) : "v"(lo), "v"(hi)); return r; }
; #define PG8_STAGE(bufoff, gbase, voff) do { _Pragma("unroll") for (int _i = 0; _i < 2; ++_i) \
;         __builtin_amdgcn_global_load_lds((const unsigned*)((const char*)(gbase) + (voff)[_i]), (LAS unsigned*)(lds + (bufoff) + ldsw + _i * 8192), 16, 0, 0); } while (0)
; #define PG8_MMA(ai, bj, At, Bt) do { __builtin_amdgcn_s_setprio(1); _Pragma("unroll") for (int m = 0; m < 4; ++m) _Pragma("unroll") for (int n = 0; n < 2; ++n) _Pragma("unroll") for (int k = 0; k < 2; ++k) \
;         acc[ai][bj][m][n] = __builtin_amdgcn_mfma_f32_16x16x32_bf16(Bt[n][k], At[m][k], acc[ai][bj][m][n], 0, 0, 0); __builtin_amdgcn_s_setprio(0); } while (0)
; #define PG8_BAR __builtin_amdgcn_s_barrier()
;     DEVI void operator()(f32x4 (&acc)[2][2][4][2], const Unit& u, int wr, int wc, int fr, int fq) const {
;     ...
;             for (int m = 0; m < 4; ++m) { bf16_t* rowp = O + (size_t)(row0 + ai * HALF + m * 16) * ldc + col0;
;                 float rstd = 1.0f; if (RS) rstd = rsqrtf(ssq[row0 + ai * HALF + m * 16] * (1.0f / 1024.0f) + EPS);
; #pragma unroll
;                 for (int bj = 0; bj < 2; ++bj) { f32x4 v0 = acc[ai][bj][m][0], v1 = acc[ai][bj][m][1];
;                     if (RS) { v0 = v0 * rstd + sh[bj][0]; v1 = v1 * rstd + sh[bj][1]; }
;                     if (ACT == 1) {
; #pragma unroll
;                         for (int j = 0; j < 4; ++j) { const float a = fmaxf(v0[j], 0.f), b = fmaxf(v1[j], 0.f); v0[j] = a * a; v1[j] = b * b; } }
;                     if (ACT == 2) {
; #pragma unroll
;                         for (int j = 0; j < 4; ++j) { v0[j] = 1.0f + __expf(-fminf(fmaxf(v0[j], -30.f), 30.f)); v1[j] = 1.0f + __expf(-fminf(fmaxf(v1[j], -30.f), 30.f)); } }
;                     u32x4 w; w.x = cvt_pk_bf16(v0[0], v0[1]); w.y = cvt_pk_bf16(v0[2], v0[3]); w.z = cvt_pk_bf16(v1[0], v1[1]); w.w = cvt_pk_bf16(v1[2], v1[3]);
;                     *(u32x4*)(rowp + bj * HALF) = w; } }
; template <class Epi>
; DEVI void gemm_phase(const int wv, LAS unsigned char* lds, const Gemm g, const Order& S, const Epi& E) {
;     ...
;             PG8_BAR; PG8_WAIT_L(0); PG8_MMA(1, 0, At, B0); PG8_BAR; PG8_SCHED;
;             PG8_STAGE(PG8_SB(1, 1), b3 + hstepB, voffB);
;             PG8_WAIT_V(6); PG8_BAR; PG8_MMA(1, 1, At, B1); PG8_BAR;
	s_waitcnt lgkmcnt(0)
	s_setprio 1
	s_waitcnt lgkmcnt(0)
	v_mfma_f32_16x16x32_bf16 v[62:65], v[140:143], v[160:163], v[62:65]
	v_mfma_f32_16x16x32_bf16 v[58:61], v[152:155], v[160:163], v[58:61]
	v_mfma_f32_16x16x32_bf16 v[46:49], v[140:143], v[168:171], v[46:49]
	v_mfma_f32_16x16x32_bf16 v[42:45], v[152:155], v[168:171], v[42:45]
	v_mfma_f32_16x16x32_bf16 v[30:33], v[140:143], v[176:179], v[30:33]
	v_mfma_f32_16x16x32_bf16 v[26:29], v[152:155], v[176:179], v[26:29]
	v_mfma_f32_16x16x32_bf16 v[14:17], v[140:143], v[184:187], v[14:17]
	v_mfma_f32_16x16x32_bf16 v[10:13], v[152:155], v[184:187], v[10:13]
	v_mfma_f32_16x16x32_bf16 v[62:65], v[148:151], v[164:167], v[62:65]
	v_mfma_f32_16x16x32_bf16 v[58:61], v[156:159], v[164:167], v[58:61]
	v_mfma_f32_16x16x32_bf16 v[46:49], v[148:151], v[172:175], v[46:49]
	v_mfma_f32_16x16x32_bf16 v[42:45], v[156:159], v[172:175], v[42:45]
	v_mfma_f32_16x16x32_bf16 v[30:33], v[148:151], v[180:183], v[30:33]
	v_mfma_f32_16x16x32_bf16 v[26:29], v[156:159], v[180:183], v[26:29]
	v_mfma_f32_16x16x32_bf16 v[14:17], v[148:151], v[188:191], v[14:17]
	v_mfma_f32_16x16x32_bf16 v[10:13], v[156:159], v[188:191], v[10:13]
	s_setprio 0
	s_barrier
	s_add_u32 s30, s30, 0x40080
	s_addc_u32 s31, s31, 0
	s_add_i32 s36, s36, s95
	v_lshl_add_u64 v[140:141], s[30:31], 0, v[0:1]
	s_mov_b32 m0, s36
	s_nop 0
	global_load_lds_dwordx4 v[140:141], off
	v_lshl_add_u64 v[140:141], s[30:31], 0, v[130:131]
	s_add_i32 m0, s36, 0x2000
	s_nop 0
	global_load_lds_dwordx4 v[140:141], off
	s_waitcnt vmcnt(6)
	s_barrier
	s_setprio 1
	v_mfma_f32_16x16x32_bf16 v[54:57], v[192:195], v[160:163], v[54:57]
	v_mfma_f32_16x16x32_bf16 v[50:53], v[204:207], v[160:163], v[50:53]
	v_mfma_f32_16x16x32_bf16 v[38:41], v[192:195], v[168:171], v[38:41]
	v_mfma_f32_16x16x32_bf16 v[34:37], v[204:207], v[168:171], v[34:37]
	v_mfma_f32_16x16x32_bf16 v[22:25], v[192:195], v[176:179], v[22:25]
	v_mfma_f32_16x16x32_bf16 v[18:21], v[204:207], v[176:179], v[18:21]
	v_mfma_f32_16x16x32_bf16 v[6:9], v[192:195], v[184:187], v[6:9]
	v_mfma_f32_16x16x32_bf16 v[2:5], v[204:207], v[184:187], v[2:5]
	v_mfma_f32_16x16x32_bf16 v[54:57], v[200:203], v[164:167], v[54:57]
	v_mfma_f32_16x16x32_bf16 v[50:53], v[208:211], v[164:167], v[50:53]
	v_mfma_f32_16x16x32_bf16 v[38:41], v[200:203], v[172:175], v[38:41]
	v_mfma_f32_16x16x32_bf16 v[34:37], v[208:211], v[172:175], v[34:37]
	v_mfma_f32_16x16x32_bf16 v[22:25], v[200:203], v[180:183], v[22:25]
	v_mfma_f32_16x16x32_bf16 v[18:21], v[208:211], v[180:183], v[18:21]
	v_mfma_f32_16x16x32_bf16 v[6:9], v[200:203], v[188:191], v[6:9]
	v_mfma_f32_16x16x32_bf16 v[2:5], v[208:211], v[188:191], v[2:5]
	s_setprio 0
	s_add_i32 s57, s57, 2
	s_add_u32 s28, s28, 0x100
	s_addc_u32 s29, s29, 0
	s_add_u32 s55, s55, 0x100
	s_addc_u32 s56, s56, 0
	s_cmp_gt_u32 s57, 13
	s_barrier
	s_cbranch_scc0 .LBB0_814
	v_max_f32_e32 v122, v122, v122
	v_med3_f32 v122, v122, s49, v238
	v_max_f32_e32 v123, v123, v123
	v_max_f32_e32 v124, v124, v124
	v_mul_f32_e32 v122, 0xbfb8aa3b, v122
	v_med3_f32 v123, v123, s49, v238
	v_med3_f32 v124, v124, s49, v238
	v_exp_f32_e32 v122, v122
	v_mul_f32_e32 v123, 0xbfb8aa3b, v123
	v_mul_f32_e32 v124, 0xbfb8aa3b, v124
	v_exp_f32_e32 v123, v123
	v_exp_f32_e32 v124, v124
	v_add_f32_e32 v149, 1.0, v122
	v_max_f32_e32 v122, v127, v127
	v_max_f32_e32 v126, v126, v126
	v_med3_f32 v122, v122, s49, v238
	v_add_f32_e32 v127, 1.0, v123
	v_max_f32_e32 v123, v128, v128
	v_add_f32_e32 v128, 1.0, v124
	v_max_f32_e32 v124, v129, v129
	v_max_f32_e32 v125, v125, v125
	v_med3_f32 v126, v126, s49, v238
	v_mul_f32_e32 v122, 0xbfb8aa3b, v122
	v_med3_f32 v123, v123, s49, v238
	v_med3_f32 v124, v124, s49, v238
	v_med3_f32 v125, v125, s49, v238
	v_max_f32_e32 v114, v114, v114
	v_max_f32_e32 v115, v115, v115
	v_max_f32_e32 v116, v116, v116
	v_mul_f32_e32 v126, 0xbfb8aa3b, v126
	v_exp_f32_e32 v122, v122
	v_mul_f32_e32 v123, 0xbfb8aa3b, v123
	v_mul_f32_e32 v124, 0xbfb8aa3b, v124
	v_mul_f32_e32 v125, 0xbfb8aa3b, v125
	v_med3_f32 v114, v114, s49, v238
	v_med3_f32 v115, v115, s49, v238
	v_med3_f32 v116, v116, s49, v238
	v_exp_f32_e32 v126, v126
	v_exp_f32_e32 v123, v123
	v_exp_f32_e32 v124, v124
	v_exp_f32_e32 v125, v125
	v_mul_f32_e32 v114, 0xbfb8aa3b, v114
	v_mul_f32_e32 v115, 0xbfb8aa3b, v115
	v_mul_f32_e32 v116, 0xbfb8aa3b, v116
	v_lshl_or_b32 v142, s10, 8, v146
	v_exp_f32_e32 v114, v114
	v_exp_f32_e32 v115, v115
	v_exp_f32_e32 v116, v116
	v_lshl_add_u32 v148, s12, 8, v144
	v_ashrrev_i32_e32 v143, 31, v142
	v_mov_b64_e32 v[140:141], s[24:25]
	s_movk_i32 s1, 0x1800
	v_mad_i64_i32 v[150:151], s[28:29], v148, s1, v[140:141]
	v_lshlrev_b64 v[142:143], 1, v[142:143]
	v_add_f32_e32 v122, 1.0, v122
	v_lshl_add_u64 v[150:151], v[150:151], 0, v[142:143]
	v_add_f32_e32 v126, 1.0, v126
	v_add_f32_e32 v123, 1.0, v123
	v_add_f32_e32 v124, 1.0, v124
	v_add_f32_e32 v125, 1.0, v125
	v_cvt_pk_bf16_f32 v122, v126, v122
	v_cvt_pk_bf16_f32 v123, v123, v124
	v_cvt_pk_bf16_f32 v124, v149, v127
	v_cvt_pk_bf16_f32 v125, v128, v125
	global_store_dwordx4 v[150:151], v[122:125], off
	v_max_f32_e32 v118, v118, v118
	v_max_f32_e32 v117, v117, v117
	v_add_f32_e32 v122, 1.0, v114
	v_max_f32_e32 v114, v119, v119
	v_add_f32_e32 v119, 1.0, v115
	v_max_f32_e32 v115, v120, v120
	v_add_f32_e32 v120, 1.0, v116
	v_max_f32_e32 v116, v121, v121
	v_med3_f32 v114, v114, s49, v238
	v_med3_f32 v115, v115, s49, v238
	v_med3_f32 v116, v116, s49, v238
	v_med3_f32 v118, v118, s49, v238
	v_mul_f32_e32 v114, 0xbfb8aa3b, v114
	v_mul_f32_e32 v115, 0xbfb8aa3b, v115
	v_mul_f32_e32 v116, 0xbfb8aa3b, v116
	v_med3_f32 v117, v117, s49, v238
	v_max_f32_e32 v106, v106, v106
	v_mul_f32_e32 v118, 0xbfb8aa3b, v118
; DEVI unsigned cvt_pk_bf16(float lo, float hi) { unsigned r; asm volatile("v_cvt_pk_bf16_f32 %0, %1, %2" : "=v"(r) : "v"(lo), "v"(hi)); return r; }
;     DEVI void operator()(f32x4 (&acc)[2][2][4][2], const Unit& u, int wr, int wc, int fr, int fq) const {
;     ...
;             for (int m = 0; m < 4; ++m) { bf16_t* rowp = O + (size_t)(row0 + ai * HALF + m * 16) * ldc + col0;
;                 float rstd = 1.0f; if (RS) rstd = rsqrtf(ssq[row0 + ai * HALF + m * 16] * (1.0f / 1024.0f) + EPS);
; #pragma unroll
;                 for (int bj = 0; bj < 2; ++bj) { f32x4 v0 = acc[ai][bj][m][0], v1 = acc[ai][bj][m][1];
;                     if (RS) { v0 = v0 * rstd + sh[bj][0]; v1 = v1 * rstd + sh[bj][1]; }
;                     if (ACT == 1) {
; #pragma unroll
;                         for (int j = 0; j < 4; ++j) { const float a = fmaxf(v0[j], 0.f), b = fmaxf(v1[j], 0.f); v0[j] = a * a; v1[j] = b * b; } }
;                     if (ACT == 2) {
; #pragma unroll
;                         for (int j = 0; j < 4; ++j) { v0[j] = 1.0f + __expf(-fminf(fmaxf(v0[j], -30.f), 30.f)); v1[j] = 1.0f + __expf(-fminf(fmaxf(v1[j], -30.f), 30.f)); } }
;                     u32x4 w; w.x = cvt_pk_bf16(v0[0], v0[1]); w.y = cvt_pk_bf16(v0[2], v0[3]); w.z = cvt_pk_bf16(v1[0], v1[1]); w.w = cvt_pk_bf16(v1[2], v1[3]);
;                     *(u32x4*)(rowp + bj * HALF) = w; } }
	v_exp_f32_e32 v114, v114
	v_exp_f32_e32 v115, v115
	v_exp_f32_e32 v116, v116
	v_mul_f32_e32 v117, 0xbfb8aa3b, v117
	v_med3_f32 v106, v106, s49, v238
	v_max_f32_e32 v107, v107, v107
	v_max_f32_e32 v108, v108, v108
	v_exp_f32_e32 v118, v118
	v_exp_f32_e32 v117, v117
	v_mul_f32_e32 v106, 0xbfb8aa3b, v106
	v_med3_f32 v107, v107, s49, v238
	v_med3_f32 v108, v108, s49, v238
	v_exp_f32_e32 v106, v106
	v_mul_f32_e32 v107, 0xbfb8aa3b, v107
	v_mul_f32_e32 v108, 0xbfb8aa3b, v108
	v_exp_f32_e32 v107, v107
	v_exp_f32_e32 v108, v108
	v_add_f32_e32 v114, 1.0, v114
	v_add_f32_e32 v115, 1.0, v115
	v_add_f32_e32 v116, 1.0, v116
	v_add_f32_e32 v118, 1.0, v118
	v_add_f32_e32 v117, 1.0, v117
	v_cvt_pk_bf16_f32 v114, v118, v114
	v_cvt_pk_bf16_f32 v115, v115, v116
	v_cvt_pk_bf16_f32 v116, v122, v119
	v_cvt_pk_bf16_f32 v117, v120, v117
	global_store_dwordx4 v[150:151], v[114:117], off offset:256
	v_max_f32_e32 v110, v110, v110
	v_max_f32_e32 v109, v109, v109
	v_add_f32_e32 v116, 1.0, v106
	v_max_f32_e32 v106, v111, v111
	v_med3_f32 v106, v106, s49, v238
	v_add_f32_e32 v111, 1.0, v107
	v_max_f32_e32 v107, v112, v112
	v_add_f32_e32 v112, 1.0, v108
	v_max_f32_e32 v108, v113, v113
	v_med3_f32 v110, v110, s49, v238
	v_mul_f32_e32 v106, 0xbfb8aa3b, v106
	v_med3_f32 v107, v107, s49, v238
	v_med3_f32 v108, v108, s49, v238
	v_med3_f32 v109, v109, s49, v238
	v_max_f32_e32 v98, v98, v98
	v_max_f32_e32 v99, v99, v99
	v_max_f32_e32 v100, v100, v100
	v_mul_f32_e32 v110, 0xbfb8aa3b, v110
	v_exp_f32_e32 v106, v106
	v_mul_f32_e32 v107, 0xbfb8aa3b, v107
	v_mul_f32_e32 v108, 0xbfb8aa3b, v108
	v_mul_f32_e32 v109, 0xbfb8aa3b, v109
	v_med3_f32 v98, v98, s49, v238
	v_med3_f32 v99, v99, s49, v238
	v_med3_f32 v100, v100, s49, v238
	v_exp_f32_e32 v110, v110
	v_exp_f32_e32 v107, v107
	v_exp_f32_e32 v108, v108
	v_exp_f32_e32 v109, v109
	v_mul_f32_e32 v98, 0xbfb8aa3b, v98
	v_mul_f32_e32 v99, 0xbfb8aa3b, v99
	v_mul_f32_e32 v100, 0xbfb8aa3b, v100
	v_exp_f32_e32 v98, v98
	v_exp_f32_e32 v99, v99
	v_exp_f32_e32 v100, v100
	v_or_b32_e32 v114, 16, v148
	v_mad_i64_i32 v[114:115], s[28:29], v114, s1, v[140:141]
	v_add_f32_e32 v106, 1.0, v106
	v_lshl_add_u64 v[114:115], v[114:115], 0, v[142:143]
	v_add_f32_e32 v110, 1.0, v110
	v_add_f32_e32 v107, 1.0, v107
	v_add_f32_e32 v108, 1.0, v108
	v_add_f32_e32 v109, 1.0, v109
	v_cvt_pk_bf16_f32 v106, v110, v106
	v_cvt_pk_bf16_f32 v107, v107, v108
	v_cvt_pk_bf16_f32 v108, v116, v111
	v_cvt_pk_bf16_f32 v109, v112, v109
	global_store_dwordx4 v[114:115], v[106:109], off
	v_max_f32_e32 v102, v102, v102
	v_max_f32_e32 v101, v101, v101
	v_add_f32_e32 v106, 1.0, v98
	v_max_f32_e32 v98, v103, v103
	v_add_f32_e32 v103, 1.0, v99
	v_max_f32_e32 v99, v104, v104
	v_add_f32_e32 v104, 1.0, v100
	v_max_f32_e32 v100, v105, v105
	v_med3_f32 v98, v98, s49, v238
	v_med3_f32 v99, v99, s49, v238
	v_med3_f32 v100, v100, s49, v238
	v_med3_f32 v102, v102, s49, v238
	v_mul_f32_e32 v98, 0xbfb8aa3b, v98
	v_mul_f32_e32 v99, 0xbfb8aa3b, v99
	v_mul_f32_e32 v100, 0xbfb8aa3b, v100
	v_med3_f32 v101, v101, s49, v238
	v_max_f32_e32 v90, v90, v90
	v_mul_f32_e32 v102, 0xbfb8aa3b, v102
	v_exp_f32_e32 v98, v98
	v_exp_f32_e32 v99, v99
	v_exp_f32_e32 v100, v100
	v_mul_f32_e32 v101, 0xbfb8aa3b, v101
	v_med3_f32 v90, v90, s49, v238
	v_max_f32_e32 v91, v91, v91
	v_max_f32_e32 v92, v92, v92
	v_exp_f32_e32 v102, v102
	v_exp_f32_e32 v101, v101
	v_mul_f32_e32 v90, 0xbfb8aa3b, v90
	v_med3_f32 v91, v91, s49, v238
	v_med3_f32 v92, v92, s49, v238
	v_exp_f32_e32 v90, v90
	v_mul_f32_e32 v91, 0xbfb8aa3b, v91
	v_mul_f32_e32 v92, 0xbfb8aa3b, v92
	v_exp_f32_e32 v91, v91
	v_exp_f32_e32 v92, v92
	v_add_f32_e32 v98, 1.0, v98
	v_add_f32_e32 v99, 1.0, v99
	v_add_f32_e32 v100, 1.0, v100
	v_add_f32_e32 v102, 1.0, v102
	v_add_f32_e32 v101, 1.0, v101
	v_cvt_pk_bf16_f32 v98, v102, v98
	v_cvt_pk_bf16_f32 v99, v99, v100
	v_cvt_pk_bf16_f32 v100, v106, v103
	v_cvt_pk_bf16_f32 v101, v104, v101
	global_store_dwordx4 v[114:115], v[98:101], off offset:256
	v_max_f32_e32 v94, v94, v94
	v_max_f32_e32 v93, v93, v93
	v_add_f32_e32 v100, 1.0, v90
	v_max_f32_e32 v90, v95, v95
	v_med3_f32 v90, v90, s49, v238
	v_add_f32_e32 v95, 1.0, v91
	v_max_f32_e32 v91, v96, v96
	v_add_f32_e32 v96, 1.0, v92
	v_max_f32_e32 v92, v97, v97
	v_med3_f32 v94, v94, s49, v238
	v_mul_f32_e32 v90, 0xbfb8aa3b, v90
	v_med3_f32 v91, v91, s49, v238
	v_med3_f32 v92, v92, s49, v238
	v_med3_f32 v93, v93, s49, v238
	v_max_f32_e32 v82, v82, v82
	v_max_f32_e32 v83, v83, v83
	v_max_f32_e32 v84, v84, v84
	v_mul_f32_e32 v94, 0xbfb8aa3b, v94
	v_exp_f32_e32 v90, v90
	v_mul_f32_e32 v91, 0xbfb8aa3b, v91
	v_mul_f32_e32 v92, 0xbfb8aa3b, v92
	v_mul_f32_e32 v93, 0xbfb8aa3b, v93
	v_med3_f32 v82, v82, s49, v238
	v_med3_f32 v83, v83, s49, v238
	v_med3_f32 v84, v84, s49, v238
	v_exp_f32_e32 v94, v94
	v_exp_f32_e32 v91, v91
	v_exp_f32_e32 v92, v92
	v_exp_f32_e32 v93, v93
	v_mul_f32_e32 v82, 0xbfb8aa3b, v82
	v_mul_f32_e32 v83, 0xbfb8aa3b, v83
	v_mul_f32_e32 v84, 0xbfb8aa3b, v84
	v_exp_f32_e32 v82, v82
	v_exp_f32_e32 v83, v83
	v_exp_f32_e32 v84, v84
	v_or_b32_e32 v98, 32, v148
	v_mad_i64_i32 v[98:99], s[28:29], v98, s1, v[140:141]
	v_add_f32_e32 v90, 1.0, v90
	v_lshl_add_u64 v[98:99], v[98:99], 0, v[142:143]
	v_add_f32_e32 v94, 1.0, v94
	v_add_f32_e32 v91, 1.0, v91
	v_add_f32_e32 v92, 1.0, v92
	v_add_f32_e32 v93, 1.0, v93
	v_cvt_pk_bf16_f32 v90, v94, v90
	v_cvt_pk_bf16_f32 v91, v91, v92
	v_cvt_pk_bf16_f32 v92, v100, v95
	v_cvt_pk_bf16_f32 v93, v96, v93
	global_store_dwordx4 v[98:99], v[90:93], off
	v_max_f32_e32 v86, v86, v86
	v_max_f32_e32 v85, v85, v85
	v_add_f32_e32 v90, 1.0, v82
	v_max_f32_e32 v82, v87, v87
	v_add_f32_e32 v87, 1.0, v83
	v_max_f32_e32 v83, v88, v88
	v_add_f32_e32 v88, 1.0, v84
; DEVI unsigned cvt_pk_bf16(float lo, float hi) { unsigned r; asm volatile("v_cvt_pk_bf16_f32 %0, %1, %2" : "=v"(r) : "v"(lo), "v"(hi)); return r; }
;     DEVI void operator()(f32x4 (&acc)[2][2][4][2], const Unit& u, int wr, int wc, int fr, int fq) const {
;     ...
;             for (int m = 0; m < 4; ++m) { bf16_t* rowp = O + (size_t)(row0 + ai * HALF + m * 16) * ldc + col0;
;                 float rstd = 1.0f; if (RS) rstd = rsqrtf(ssq[row0 + ai * HALF + m * 16] * (1.0f / 1024.0f) + EPS);
; #pragma unroll
;                 for (int bj = 0; bj < 2; ++bj) { f32x4 v0 = acc[ai][bj][m][0], v1 = acc[ai][bj][m][1];
;                     if (RS) { v0 = v0 * rstd + sh[bj][0]; v1 = v1 * rstd + sh[bj][1]; }
;                     if (ACT == 1) {
; #pragma unroll
;                         for (int j = 0; j < 4; ++j) { const float a = fmaxf(v0[j], 0.f), b = fmaxf(v1[j], 0.f); v0[j] = a * a; v1[j] = b * b; } }
;                     if (ACT == 2) {
; #pragma unroll
;                         for (int j = 0; j < 4; ++j) { v0[j] = 1.0f + __expf(-fminf(fmaxf(v0[j], -30.f), 30.f)); v1[j] = 1.0f + __expf(-fminf(fmaxf(v1[j], -30.f), 30.f)); } }
;                     u32x4 w; w.x = cvt_pk_bf16(v0[0], v0[1]); w.y = cvt_pk_bf16(v0[2], v0[3]); w.z = cvt_pk_bf16(v1[0], v1[1]); w.w = cvt_pk_bf16(v1[2], v1[3]);
;                     *(u32x4*)(rowp + bj * HALF) = w; } }
	v_max_f32_e32 v84, v89, v89
	v_med3_f32 v82, v82, s49, v238
	v_med3_f32 v83, v83, s49, v238
	v_med3_f32 v84, v84, s49, v238
	v_med3_f32 v86, v86, s49, v238
	v_mul_f32_e32 v82, 0xbfb8aa3b, v82
	v_mul_f32_e32 v83, 0xbfb8aa3b, v83
	v_mul_f32_e32 v84, 0xbfb8aa3b, v84
	v_med3_f32 v85, v85, s49, v238
	v_max_f32_e32 v74, v74, v74
	v_mul_f32_e32 v86, 0xbfb8aa3b, v86
	v_exp_f32_e32 v82, v82
	v_exp_f32_e32 v83, v83
	v_exp_f32_e32 v84, v84
	v_mul_f32_e32 v85, 0xbfb8aa3b, v85
	v_med3_f32 v74, v74, s49, v238
	v_max_f32_e32 v75, v75, v75
	v_max_f32_e32 v76, v76, v76
	v_exp_f32_e32 v86, v86
	v_exp_f32_e32 v85, v85
	v_mul_f32_e32 v74, 0xbfb8aa3b, v74
	v_med3_f32 v75, v75, s49, v238
	v_med3_f32 v76, v76, s49, v238
	v_exp_f32_e32 v74, v74
	v_mul_f32_e32 v75, 0xbfb8aa3b, v75
	v_mul_f32_e32 v76, 0xbfb8aa3b, v76
	v_exp_f32_e32 v75, v75
	v_exp_f32_e32 v76, v76
	v_add_f32_e32 v82, 1.0, v82
	v_add_f32_e32 v83, 1.0, v83
	v_add_f32_e32 v84, 1.0, v84
	v_add_f32_e32 v86, 1.0, v86
	v_add_f32_e32 v85, 1.0, v85
	v_cvt_pk_bf16_f32 v82, v86, v82
	v_cvt_pk_bf16_f32 v83, v83, v84
	v_cvt_pk_bf16_f32 v84, v90, v87
	v_cvt_pk_bf16_f32 v85, v88, v85
	global_store_dwordx4 v[98:99], v[82:85], off offset:256
	v_max_f32_e32 v78, v78, v78
	v_max_f32_e32 v77, v77, v77
	v_add_f32_e32 v84, 1.0, v74
	v_max_f32_e32 v74, v79, v79
	v_med3_f32 v74, v74, s49, v238
	v_add_f32_e32 v79, 1.0, v75
	v_max_f32_e32 v75, v80, v80
	v_add_f32_e32 v80, 1.0, v76
	v_max_f32_e32 v76, v81, v81
	v_med3_f32 v78, v78, s49, v238
	v_mul_f32_e32 v74, 0xbfb8aa3b, v74
	v_med3_f32 v75, v75, s49, v238
	v_med3_f32 v76, v76, s49, v238
	v_med3_f32 v77, v77, s49, v238
	v_max_f32_e32 v66, v66, v66
	v_max_f32_e32 v67, v67, v67
	v_max_f32_e32 v68, v68, v68
	v_mul_f32_e32 v78, 0xbfb8aa3b, v78
	v_exp_f32_e32 v74, v74
	v_mul_f32_e32 v75, 0xbfb8aa3b, v75
	v_mul_f32_e32 v76, 0xbfb8aa3b, v76
	v_mul_f32_e32 v77, 0xbfb8aa3b, v77
	v_med3_f32 v66, v66, s49, v238
	v_med3_f32 v67, v67, s49, v238
	v_med3_f32 v68, v68, s49, v238
	v_exp_f32_e32 v78, v78
	v_exp_f32_e32 v75, v75
	v_exp_f32_e32 v76, v76
	v_exp_f32_e32 v77, v77
	v_mul_f32_e32 v66, 0xbfb8aa3b, v66
	v_mul_f32_e32 v67, 0xbfb8aa3b, v67
	v_mul_f32_e32 v68, 0xbfb8aa3b, v68
	v_exp_f32_e32 v66, v66
	v_exp_f32_e32 v67, v67
	v_exp_f32_e32 v68, v68
	v_or_b32_e32 v82, 48, v148
	v_mad_i64_i32 v[82:83], s[28:29], v82, s1, v[140:141]
	v_add_f32_e32 v74, 1.0, v74
	v_lshl_add_u64 v[82:83], v[82:83], 0, v[142:143]
	v_add_f32_e32 v78, 1.0, v78
	v_add_f32_e32 v75, 1.0, v75
	v_add_f32_e32 v76, 1.0, v76
	v_add_f32_e32 v77, 1.0, v77
	v_cvt_pk_bf16_f32 v74, v78, v74
	v_cvt_pk_bf16_f32 v75, v75, v76
	v_cvt_pk_bf16_f32 v76, v84, v79
	v_cvt_pk_bf16_f32 v77, v80, v77
	global_store_dwordx4 v[82:83], v[74:77], off
	v_max_f32_e32 v70, v70, v70
	v_max_f32_e32 v69, v69, v69
	v_add_f32_e32 v74, 1.0, v66
	v_max_f32_e32 v66, v71, v71
	v_add_f32_e32 v71, 1.0, v67
	v_max_f32_e32 v67, v72, v72
	v_add_f32_e32 v72, 1.0, v68
	v_max_f32_e32 v68, v73, v73
	v_med3_f32 v66, v66, s49, v238
	v_med3_f32 v67, v67, s49, v238
	v_med3_f32 v68, v68, s49, v238
	v_med3_f32 v70, v70, s49, v238
	v_mul_f32_e32 v66, 0xbfb8aa3b, v66
	v_mul_f32_e32 v67, 0xbfb8aa3b, v67
	v_mul_f32_e32 v68, 0xbfb8aa3b, v68
	v_med3_f32 v69, v69, s49, v238
	v_max_f32_e32 v58, v58, v58
	v_mul_f32_e32 v70, 0xbfb8aa3b, v70
	v_exp_f32_e32 v66, v66
	v_exp_f32_e32 v67, v67
	v_exp_f32_e32 v68, v68
	v_mul_f32_e32 v69, 0xbfb8aa3b, v69
	v_med3_f32 v58, v58, s49, v238
	v_max_f32_e32 v59, v59, v59
	v_max_f32_e32 v60, v60, v60
	v_exp_f32_e32 v70, v70
	v_exp_f32_e32 v69, v69
	v_mul_f32_e32 v58, 0xbfb8aa3b, v58
	v_med3_f32 v59, v59, s49, v238
	v_med3_f32 v60, v60, s49, v238
	v_exp_f32_e32 v58, v58
	v_mul_f32_e32 v59, 0xbfb8aa3b, v59
	v_mul_f32_e32 v60, 0xbfb8aa3b, v60
	v_exp_f32_e32 v59, v59
	v_exp_f32_e32 v60, v60
	v_add_f32_e32 v66, 1.0, v66
	v_add_f32_e32 v67, 1.0, v67
	v_add_f32_e32 v68, 1.0, v68
	v_add_f32_e32 v70, 1.0, v70
	v_add_f32_e32 v69, 1.0, v69
	v_cvt_pk_bf16_f32 v66, v70, v66
	v_cvt_pk_bf16_f32 v67, v67, v68
	v_cvt_pk_bf16_f32 v68, v74, v71
	v_cvt_pk_bf16_f32 v69, v72, v69
	global_store_dwordx4 v[82:83], v[66:69], off offset:256
	v_max_f32_e32 v62, v62, v62
	v_max_f32_e32 v61, v61, v61
	v_add_f32_e32 v68, 1.0, v58
	v_max_f32_e32 v58, v63, v63
	v_med3_f32 v58, v58, s49, v238
	v_add_f32_e32 v63, 1.0, v59
	v_max_f32_e32 v59, v64, v64
	v_add_f32_e32 v64, 1.0, v60
	v_max_f32_e32 v60, v65, v65
	v_med3_f32 v62, v62, s49, v238
	v_mul_f32_e32 v58, 0xbfb8aa3b, v58
	v_med3_f32 v59, v59, s49, v238
	v_med3_f32 v60, v60, s49, v238
	v_med3_f32 v61, v61, s49, v238
	v_max_f32_e32 v50, v50, v50
	v_max_f32_e32 v51, v51, v51
	v_max_f32_e32 v52, v52, v52
	v_mul_f32_e32 v62, 0xbfb8aa3b, v62
	v_exp_f32_e32 v58, v58
	v_mul_f32_e32 v59, 0xbfb8aa3b, v59
	v_mul_f32_e32 v60, 0xbfb8aa3b, v60
	v_mul_f32_e32 v61, 0xbfb8aa3b, v61
	v_med3_f32 v50, v50, s49, v238
	v_med3_f32 v51, v51, s49, v238
	v_med3_f32 v52, v52, s49, v238
	v_exp_f32_e32 v62, v62
	v_exp_f32_e32 v59, v59
	v_exp_f32_e32 v60, v60
	v_exp_f32_e32 v61, v61
	v_mul_f32_e32 v50, 0xbfb8aa3b, v50
	v_mul_f32_e32 v51, 0xbfb8aa3b, v51
	v_mul_f32_e32 v52, 0xbfb8aa3b, v52
	v_exp_f32_e32 v50, v50
	v_exp_f32_e32 v51, v51
	v_exp_f32_e32 v52, v52
	v_add_u32_e32 v66, 0x80, v148
	v_mad_i64_i32 v[66:67], s[28:29], v66, s1, v[140:141]
	v_add_f32_e32 v58, 1.0, v58
	v_lshl_add_u64 v[66:67], v[66:67], 0, v[142:143]
	v_add_f32_e32 v62, 1.0, v62
	v_add_f32_e32 v59, 1.0, v59
	v_add_f32_e32 v60, 1.0, v60
	v_add_f32_e32 v61, 1.0, v61
	v_cvt_pk_bf16_f32 v58, v62, v58
	v_cvt_pk_bf16_f32 v59, v59, v60
	v_cvt_pk_bf16_f32 v60, v68, v63
	v_cvt_pk_bf16_f32 v61, v64, v61
	global_store_dwordx4 v[66:67], v[58:61], off
	v_max_f32_e32 v54, v54, v54
; DEVI unsigned cvt_pk_bf16(float lo, float hi) { unsigned r; asm volatile("v_cvt_pk_bf16_f32 %0, %1, %2" : "=v"(r) : "v"(lo), "v"(hi)); return r; }
;     DEVI void operator()(f32x4 (&acc)[2][2][4][2], const Unit& u, int wr, int wc, int fr, int fq) const {
;     ...
;             for (int m = 0; m < 4; ++m) { bf16_t* rowp = O + (size_t)(row0 + ai * HALF + m * 16) * ldc + col0;
;                 float rstd = 1.0f; if (RS) rstd = rsqrtf(ssq[row0 + ai * HALF + m * 16] * (1.0f / 1024.0f) + EPS);
; #pragma unroll
;                 for (int bj = 0; bj < 2; ++bj) { f32x4 v0 = acc[ai][bj][m][0], v1 = acc[ai][bj][m][1];
;                     if (RS) { v0 = v0 * rstd + sh[bj][0]; v1 = v1 * rstd + sh[bj][1]; }
;                     if (ACT == 1) {
; #pragma unroll
;                         for (int j = 0; j < 4; ++j) { const float a = fmaxf(v0[j], 0.f), b = fmaxf(v1[j], 0.f); v0[j] = a * a; v1[j] = b * b; } }
;                     if (ACT == 2) {
; #pragma unroll
;                         for (int j = 0; j < 4; ++j) { v0[j] = 1.0f + __expf(-fminf(fmaxf(v0[j], -30.f), 30.f)); v1[j] = 1.0f + __expf(-fminf(fmaxf(v1[j], -30.f), 30.f)); } }
;                     u32x4 w; w.x = cvt_pk_bf16(v0[0], v0[1]); w.y = cvt_pk_bf16(v0[2], v0[3]); w.z = cvt_pk_bf16(v1[0], v1[1]); w.w = cvt_pk_bf16(v1[2], v1[3]);
;                     *(u32x4*)(rowp + bj * HALF) = w; } }
	v_max_f32_e32 v53, v53, v53
	v_add_f32_e32 v58, 1.0, v50
	v_max_f32_e32 v50, v55, v55
	v_add_f32_e32 v55, 1.0, v51
	v_max_f32_e32 v51, v56, v56
	v_add_f32_e32 v56, 1.0, v52
	v_max_f32_e32 v52, v57, v57
	v_med3_f32 v50, v50, s49, v238
	v_med3_f32 v51, v51, s49, v238
	v_med3_f32 v52, v52, s49, v238
	v_med3_f32 v54, v54, s49, v238
	v_mul_f32_e32 v50, 0xbfb8aa3b, v50
	v_mul_f32_e32 v51, 0xbfb8aa3b, v51
	v_mul_f32_e32 v52, 0xbfb8aa3b, v52
	v_med3_f32 v53, v53, s49, v238
	v_max_f32_e32 v42, v42, v42
	v_mul_f32_e32 v54, 0xbfb8aa3b, v54
	v_exp_f32_e32 v50, v50
	v_exp_f32_e32 v51, v51
	v_exp_f32_e32 v52, v52
	v_mul_f32_e32 v53, 0xbfb8aa3b, v53
	v_med3_f32 v42, v42, s49, v238
	v_max_f32_e32 v43, v43, v43
	v_max_f32_e32 v44, v44, v44
	v_exp_f32_e32 v54, v54
	v_exp_f32_e32 v53, v53
	v_mul_f32_e32 v42, 0xbfb8aa3b, v42
	v_med3_f32 v43, v43, s49, v238
	v_med3_f32 v44, v44, s49, v238
	v_exp_f32_e32 v42, v42
	v_mul_f32_e32 v43, 0xbfb8aa3b, v43
	v_mul_f32_e32 v44, 0xbfb8aa3b, v44
	v_exp_f32_e32 v43, v43
	v_exp_f32_e32 v44, v44
	v_add_f32_e32 v50, 1.0, v50
	v_add_f32_e32 v51, 1.0, v51
	v_add_f32_e32 v52, 1.0, v52
	v_add_f32_e32 v54, 1.0, v54
	v_add_f32_e32 v53, 1.0, v53
	v_cvt_pk_bf16_f32 v50, v54, v50
	v_cvt_pk_bf16_f32 v51, v51, v52
	v_cvt_pk_bf16_f32 v52, v58, v55
	v_cvt_pk_bf16_f32 v53, v56, v53
	global_store_dwordx4 v[66:67], v[50:53], off offset:256
	v_max_f32_e32 v46, v46, v46
	v_max_f32_e32 v45, v45, v45
	v_add_f32_e32 v52, 1.0, v42
	v_max_f32_e32 v42, v47, v47
	v_med3_f32 v42, v42, s49, v238
	v_add_f32_e32 v47, 1.0, v43
	v_max_f32_e32 v43, v48, v48
	v_add_f32_e32 v48, 1.0, v44
	v_max_f32_e32 v44, v49, v49
	v_med3_f32 v46, v46, s49, v238
	v_mul_f32_e32 v42, 0xbfb8aa3b, v42
	v_med3_f32 v43, v43, s49, v238
	v_med3_f32 v44, v44, s49, v238
	v_med3_f32 v45, v45, s49, v238
	v_max_f32_e32 v34, v34, v34
	v_max_f32_e32 v35, v35, v35
	v_max_f32_e32 v36, v36, v36
	v_mul_f32_e32 v46, 0xbfb8aa3b, v46
	v_exp_f32_e32 v42, v42
	v_mul_f32_e32 v43, 0xbfb8aa3b, v43
	v_mul_f32_e32 v44, 0xbfb8aa3b, v44
	v_mul_f32_e32 v45, 0xbfb8aa3b, v45
	v_med3_f32 v34, v34, s49, v238
	v_med3_f32 v35, v35, s49, v238
	v_med3_f32 v36, v36, s49, v238
	v_exp_f32_e32 v46, v46
	v_exp_f32_e32 v43, v43
	v_exp_f32_e32 v44, v44
	v_exp_f32_e32 v45, v45
	v_mul_f32_e32 v34, 0xbfb8aa3b, v34
	v_mul_f32_e32 v35, 0xbfb8aa3b, v35
	v_mul_f32_e32 v36, 0xbfb8aa3b, v36
	v_exp_f32_e32 v34, v34
	v_exp_f32_e32 v35, v35
	v_exp_f32_e32 v36, v36
	v_add_u32_e32 v50, 0x90, v148
	v_mad_i64_i32 v[50:51], s[28:29], v50, s1, v[140:141]
	v_add_f32_e32 v42, 1.0, v42
	v_lshl_add_u64 v[50:51], v[50:51], 0, v[142:143]
	v_add_f32_e32 v46, 1.0, v46
	v_add_f32_e32 v43, 1.0, v43
	v_add_f32_e32 v44, 1.0, v44
	v_add_f32_e32 v45, 1.0, v45
	v_cvt_pk_bf16_f32 v42, v46, v42
	v_cvt_pk_bf16_f32 v43, v43, v44
	v_cvt_pk_bf16_f32 v44, v52, v47
	v_cvt_pk_bf16_f32 v45, v48, v45
	global_store_dwordx4 v[50:51], v[42:45], off
	v_max_f32_e32 v38, v38, v38
	v_max_f32_e32 v37, v37, v37
	v_add_f32_e32 v42, 1.0, v34
	v_max_f32_e32 v34, v39, v39
	v_add_f32_e32 v39, 1.0, v35
	v_max_f32_e32 v35, v40, v40
	v_add_f32_e32 v40, 1.0, v36
	v_max_f32_e32 v36, v41, v41
	v_med3_f32 v34, v34, s49, v238
	v_med3_f32 v35, v35, s49, v238
	v_med3_f32 v36, v36, s49, v238
	v_med3_f32 v38, v38, s49, v238
	v_mul_f32_e32 v34, 0xbfb8aa3b, v34
	v_mul_f32_e32 v35, 0xbfb8aa3b, v35
	v_mul_f32_e32 v36, 0xbfb8aa3b, v36
	v_med3_f32 v37, v37, s49, v238
	v_max_f32_e32 v26, v26, v26
	v_mul_f32_e32 v38, 0xbfb8aa3b, v38
	v_exp_f32_e32 v34, v34
	v_exp_f32_e32 v35, v35
	v_exp_f32_e32 v36, v36
	v_mul_f32_e32 v37, 0xbfb8aa3b, v37
	v_med3_f32 v26, v26, s49, v238
	v_max_f32_e32 v27, v27, v27
	v_max_f32_e32 v28, v28, v28
	v_exp_f32_e32 v38, v38
	v_exp_f32_e32 v37, v37
	v_mul_f32_e32 v26, 0xbfb8aa3b, v26
	v_med3_f32 v27, v27, s49, v238
	v_med3_f32 v28, v28, s49, v238
	v_exp_f32_e32 v26, v26
	v_mul_f32_e32 v27, 0xbfb8aa3b, v27
	v_mul_f32_e32 v28, 0xbfb8aa3b, v28
	v_exp_f32_e32 v27, v27
	v_exp_f32_e32 v28, v28
	v_add_f32_e32 v34, 1.0, v34
	v_add_f32_e32 v35, 1.0, v35
	v_add_f32_e32 v36, 1.0, v36
	v_add_f32_e32 v38, 1.0, v38
	v_add_f32_e32 v37, 1.0, v37
	v_cvt_pk_bf16_f32 v34, v38, v34
	v_cvt_pk_bf16_f32 v35, v35, v36
	v_cvt_pk_bf16_f32 v36, v42, v39
	v_cvt_pk_bf16_f32 v37, v40, v37
	global_store_dwordx4 v[50:51], v[34:37], off offset:256
	v_max_f32_e32 v30, v30, v30
	v_max_f32_e32 v29, v29, v29
	v_add_f32_e32 v36, 1.0, v26
	v_max_f32_e32 v26, v31, v31
	v_med3_f32 v26, v26, s49, v238
	v_add_f32_e32 v31, 1.0, v27
	v_max_f32_e32 v27, v32, v32
	v_add_f32_e32 v32, 1.0, v28
	v_max_f32_e32 v28, v33, v33
	v_med3_f32 v30, v30, s49, v238
	v_mul_f32_e32 v26, 0xbfb8aa3b, v26
	v_med3_f32 v27, v27, s49, v238
	v_med3_f32 v28, v28, s49, v238
	v_med3_f32 v29, v29, s49, v238
	v_max_f32_e32 v18, v18, v18
	v_max_f32_e32 v19, v19, v19
	v_max_f32_e32 v20, v20, v20
	v_mul_f32_e32 v30, 0xbfb8aa3b, v30
	v_exp_f32_e32 v26, v26
	v_mul_f32_e32 v27, 0xbfb8aa3b, v27
	v_mul_f32_e32 v28, 0xbfb8aa3b, v28
; DEVI unsigned cvt_pk_bf16(float lo, float hi) { unsigned r; asm volatile("v_cvt_pk_bf16_f32 %0, %1, %2" : "=v"(r) : "v"(lo), "v"(hi)); return r; }
;     DEVI void operator()(f32x4 (&acc)[2][2][4][2], const Unit& u, int wr, int wc, int fr, int fq) const {
;     ...
;             for (int m = 0; m < 4; ++m) { bf16_t* rowp = O + (size_t)(row0 + ai * HALF + m * 16) * ldc + col0;
;                 float rstd = 1.0f; if (RS) rstd = rsqrtf(ssq[row0 + ai * HALF + m * 16] * (1.0f / 1024.0f) + EPS);
; #pragma unroll
;                 for (int bj = 0; bj < 2; ++bj) { f32x4 v0 = acc[ai][bj][m][0], v1 = acc[ai][bj][m][1];
;                     if (RS) { v0 = v0 * rstd + sh[bj][0]; v1 = v1 * rstd + sh[bj][1]; }
;                     if (ACT == 1) {
; #pragma unroll
;                         for (int j = 0; j < 4; ++j) { const float a = fmaxf(v0[j], 0.f), b = fmaxf(v1[j], 0.f); v0[j] = a * a; v1[j] = b * b; } }
;                     if (ACT == 2) {
; #pragma unroll
;                         for (int j = 0; j < 4; ++j) { v0[j] = 1.0f + __expf(-fminf(fmaxf(v0[j], -30.f), 30.f)); v1[j] = 1.0f + __expf(-fminf(fmaxf(v1[j], -30.f), 30.f)); } }
;                     u32x4 w; w.x = cvt_pk_bf16(v0[0], v0[1]); w.y = cvt_pk_bf16(v0[2], v0[3]); w.z = cvt_pk_bf16(v1[0], v1[1]); w.w = cvt_pk_bf16(v1[2], v1[3]);
;                     *(u32x4*)(rowp + bj * HALF) = w; } }
; template <class Epi>
; DEVI void gemm_phase(const int wv, LAS unsigned char* lds, const Gemm g, const Order& S, const Epi& E) {
;     ...
;         if (!has_next) break;
;         cur = nxt; cA = nA; cB = nB; ++ui;
	v_mul_f32_e32 v29, 0xbfb8aa3b, v29
	v_med3_f32 v18, v18, s49, v238
	v_med3_f32 v19, v19, s49, v238
	v_med3_f32 v20, v20, s49, v238
	v_exp_f32_e32 v30, v30
	v_exp_f32_e32 v27, v27
	v_exp_f32_e32 v28, v28
	v_exp_f32_e32 v29, v29
	v_mul_f32_e32 v18, 0xbfb8aa3b, v18
	v_mul_f32_e32 v19, 0xbfb8aa3b, v19
	v_mul_f32_e32 v20, 0xbfb8aa3b, v20
	v_exp_f32_e32 v18, v18
	v_exp_f32_e32 v19, v19
	v_exp_f32_e32 v20, v20
	v_add_u32_e32 v34, 0xa0, v148
	v_mad_i64_i32 v[34:35], s[28:29], v34, s1, v[140:141]
	v_add_f32_e32 v26, 1.0, v26
	v_lshl_add_u64 v[34:35], v[34:35], 0, v[142:143]
	v_add_f32_e32 v30, 1.0, v30
	v_add_f32_e32 v27, 1.0, v27
	v_add_f32_e32 v28, 1.0, v28
	v_add_f32_e32 v29, 1.0, v29
	v_cvt_pk_bf16_f32 v26, v30, v26
	v_cvt_pk_bf16_f32 v27, v27, v28
	v_cvt_pk_bf16_f32 v28, v36, v31
	v_cvt_pk_bf16_f32 v29, v32, v29
	global_store_dwordx4 v[34:35], v[26:29], off
	v_max_f32_e32 v22, v22, v22
	v_max_f32_e32 v21, v21, v21
	v_add_f32_e32 v26, 1.0, v18
	v_max_f32_e32 v18, v23, v23
	v_add_f32_e32 v23, 1.0, v19
	v_max_f32_e32 v19, v24, v24
	v_add_f32_e32 v24, 1.0, v20
	v_max_f32_e32 v20, v25, v25
	v_med3_f32 v18, v18, s49, v238
	v_med3_f32 v19, v19, s49, v238
	v_med3_f32 v20, v20, s49, v238
	v_med3_f32 v22, v22, s49, v238
	v_mul_f32_e32 v18, 0xbfb8aa3b, v18
	v_mul_f32_e32 v19, 0xbfb8aa3b, v19
	v_mul_f32_e32 v20, 0xbfb8aa3b, v20
	v_med3_f32 v21, v21, s49, v238
	v_max_f32_e32 v10, v10, v10
	v_mul_f32_e32 v22, 0xbfb8aa3b, v22
	v_exp_f32_e32 v18, v18
	v_exp_f32_e32 v19, v19
	v_exp_f32_e32 v20, v20
	v_mul_f32_e32 v21, 0xbfb8aa3b, v21
	v_med3_f32 v10, v10, s49, v238
	v_max_f32_e32 v11, v11, v11
	v_max_f32_e32 v12, v12, v12
	v_exp_f32_e32 v22, v22
	v_exp_f32_e32 v21, v21
	v_mul_f32_e32 v10, 0xbfb8aa3b, v10
	v_med3_f32 v11, v11, s49, v238
	v_med3_f32 v12, v12, s49, v238
	v_exp_f32_e32 v10, v10
	v_mul_f32_e32 v11, 0xbfb8aa3b, v11
	v_mul_f32_e32 v12, 0xbfb8aa3b, v12
	v_exp_f32_e32 v11, v11
	v_exp_f32_e32 v12, v12
	v_add_f32_e32 v18, 1.0, v18
	v_add_f32_e32 v19, 1.0, v19
	v_add_f32_e32 v20, 1.0, v20
	v_add_f32_e32 v22, 1.0, v22
	v_add_f32_e32 v21, 1.0, v21
	v_cvt_pk_bf16_f32 v18, v22, v18
	v_cvt_pk_bf16_f32 v19, v19, v20
	v_cvt_pk_bf16_f32 v20, v26, v23
	v_cvt_pk_bf16_f32 v21, v24, v21
	global_store_dwordx4 v[34:35], v[18:21], off offset:256
	v_max_f32_e32 v14, v14, v14
	v_max_f32_e32 v13, v13, v13
	v_add_f32_e32 v20, 1.0, v10
	v_max_f32_e32 v10, v15, v15
	v_med3_f32 v10, v10, s49, v238
	v_add_f32_e32 v15, 1.0, v11
	v_max_f32_e32 v11, v16, v16
	v_add_f32_e32 v16, 1.0, v12
	v_max_f32_e32 v12, v17, v17
	v_med3_f32 v14, v14, s49, v238
	v_mul_f32_e32 v10, 0xbfb8aa3b, v10
	v_med3_f32 v11, v11, s49, v238
	v_med3_f32 v12, v12, s49, v238
	v_med3_f32 v13, v13, s49, v238
	v_max_f32_e32 v2, v2, v2
	v_max_f32_e32 v3, v3, v3
	v_max_f32_e32 v4, v4, v4
	v_mul_f32_e32 v14, 0xbfb8aa3b, v14
	v_exp_f32_e32 v10, v10
	v_mul_f32_e32 v11, 0xbfb8aa3b, v11
	v_mul_f32_e32 v12, 0xbfb8aa3b, v12
	v_mul_f32_e32 v13, 0xbfb8aa3b, v13
	v_med3_f32 v2, v2, s49, v238
	v_med3_f32 v3, v3, s49, v238
	v_med3_f32 v4, v4, s49, v238
	v_exp_f32_e32 v14, v14
	v_exp_f32_e32 v11, v11
	v_exp_f32_e32 v12, v12
	v_exp_f32_e32 v13, v13
	v_mul_f32_e32 v2, 0xbfb8aa3b, v2
	v_mul_f32_e32 v3, 0xbfb8aa3b, v3
	v_mul_f32_e32 v4, 0xbfb8aa3b, v4
	v_exp_f32_e32 v2, v2
	v_exp_f32_e32 v3, v3
	v_exp_f32_e32 v4, v4
	v_add_u32_e32 v18, 0xb0, v148
	v_mad_i64_i32 v[18:19], s[28:29], v18, s1, v[140:141]
	v_add_f32_e32 v10, 1.0, v10
	v_lshl_add_u64 v[18:19], v[18:19], 0, v[142:143]
	v_add_f32_e32 v14, 1.0, v14
	v_add_f32_e32 v11, 1.0, v11
	v_add_f32_e32 v12, 1.0, v12
	v_add_f32_e32 v13, 1.0, v13
	v_cvt_pk_bf16_f32 v10, v14, v10
	v_cvt_pk_bf16_f32 v11, v11, v12
	v_cvt_pk_bf16_f32 v12, v20, v15
	v_cvt_pk_bf16_f32 v13, v16, v13
	global_store_dwordx4 v[18:19], v[10:13], off
	v_max_f32_e32 v5, v5, v5
	v_max_f32_e32 v6, v6, v6
	v_add_f32_e32 v10, 1.0, v2
	v_max_f32_e32 v2, v7, v7
	v_add_f32_e32 v7, 1.0, v3
	v_max_f32_e32 v3, v8, v8
	v_add_f32_e32 v8, 1.0, v4
	v_max_f32_e32 v4, v9, v9
	v_med3_f32 v2, v2, s49, v238
	v_med3_f32 v3, v3, s49, v238
	v_med3_f32 v4, v4, s49, v238
	v_med3_f32 v5, v5, s49, v238
	v_med3_f32 v6, v6, s49, v238
	v_mul_f32_e32 v2, 0xbfb8aa3b, v2
	v_mul_f32_e32 v3, 0xbfb8aa3b, v3
	v_mul_f32_e32 v4, 0xbfb8aa3b, v4
	v_mul_f32_e32 v5, 0xbfb8aa3b, v5
	v_mul_f32_e32 v6, 0xbfb8aa3b, v6
	v_exp_f32_e32 v2, v2
	v_exp_f32_e32 v3, v3
	v_exp_f32_e32 v4, v4
	v_exp_f32_e32 v5, v5
	v_exp_f32_e32 v6, v6
	s_movk_i32 s47, 0x1800
	v_add_f32_e32 v2, 1.0, v2
	v_add_f32_e32 v3, 1.0, v3
	v_add_f32_e32 v4, 1.0, v4
	v_add_f32_e32 v5, 1.0, v5
	s_and_b64 vcc, exec, s[6:7]
	s_mov_b32 s10, s0
	s_mov_b32 s12, s2
	s_mov_b64 s[30:31], s[8:9]
	s_mov_b64 s[28:29], s[4:5]
	s_movk_i32 s55, 0xc00
	v_add_f32_e32 v6, 1.0, v6
	v_cvt_pk_bf16_f32 v2, v6, v2
	v_cvt_pk_bf16_f32 v3, v3, v4
	v_cvt_pk_bf16_f32 v4, v10, v7
	v_cvt_pk_bf16_f32 v5, v8, v5
	global_store_dwordx4 v[18:19], v[2:5], off offset:256
	s_cbranch_vccz .LBB0_809
	s_branch .LBB0_817

; __global__ void __launch_bounds__(NTHREADS) mega(Params p) {
;     extern __shared__ __attribute__((aligned(16))) unsigned char lds_raw[];
	.amdhsa_kernel _Z4mega6Params
		.amdhsa_group_segment_fixed_size 0
		.amdhsa_private_segment_fixed_size 0
		.amdhsa_kernarg_size 448
		.amdhsa_user_sgpr_count 2
		.amdhsa_user_sgpr_dispatch_ptr 0
		.amdhsa_user_sgpr_queue_ptr 0
		.amdhsa_user_sgpr_kernarg_segment_ptr 1
		.amdhsa_user_sgpr_dispatch_id 0
		.amdhsa_user_sgpr_kernarg_preload_length 0
		.amdhsa_user_sgpr_kernarg_preload_offset 0
		.amdhsa_user_sgpr_private_segment_size 0
		.amdhsa_uses_dynamic_stack 0
		.amdhsa_enable_private_segment 0
		.amdhsa_system_sgpr_workgroup_id_x 1
		.amdhsa_system_sgpr_workgroup_id_y 0
		.amdhsa_system_sgpr_workgroup_id_z 0
		.amdhsa_system_sgpr_workgroup_info 0
		.amdhsa_system_vgpr_workitem_id 2
		.amdhsa_next_free_vgpr 254
		.amdhsa_next_free_sgpr 100
		.amdhsa_accum_offset 256
		.amdhsa_reserve_vcc 1
		.amdhsa_float_round_mode_32 0
		.amdhsa_float_round_mode_16_64 0
		.amdhsa_float_denorm_mode_32 3
		.amdhsa_float_denorm_mode_16_64 3
		.amdhsa_dx10_clamp 1
		.amdhsa_ieee_mode 1
		.amdhsa_fp16_overflow 0
		.amdhsa_tg_split 0
		.amdhsa_exception_fp_ieee_invalid_op 0
		.amdhsa_exception_fp_denorm_src 0
		.amdhsa_exception_fp_ieee_div_zero 0
		.amdhsa_exception_fp_ieee_overflow 0
		.amdhsa_exception_fp_ieee_underflow 0
		.amdhsa_exception_fp_ieee_inexact 0
		.amdhsa_exception_int_div_zero 0
	.end_amdhsa_kernel

; __global__ void __launch_bounds__(NTHREADS) mega(Params p) {
;     extern __shared__ __attribute__((aligned(16))) unsigned char lds_raw[];
amdhsa.kernels:
  - .agpr_count:     0
    .args:
      - .offset:         0
        .size:           192
        .value_kind:     by_value
      - .offset:         192
        .size:           4
        .value_kind:     hidden_block_count_x
      - .offset:         196
        .size:           4
        .value_kind:     hidden_block_count_y
      - .offset:         200
        .size:           4
        .value_kind:     hidden_block_count_z
      - .offset:         204
        .size:           2
        .value_kind:     hidden_group_size_x
      - .offset:         206
        .size:           2
        .value_kind:     hidden_group_size_y
      - .offset:         208
        .size:           2
        .value_kind:     hidden_group_size_z
      - .offset:         210
        .size:           2
        .value_kind:     hidden_remainder_x
      - .offset:         212
        .size:           2
        .value_kind:     hidden_remainder_y
      - .offset:         214
        .size:           2
        .value_kind:     hidden_remainder_z
      - .offset:         232
        .size:           8
        .value_kind:     hidden_global_offset_x
      - .offset:         240
        .size:           8
        .value_kind:     hidden_global_offset_y
      - .offset:         248
        .size:           8
        .value_kind:     hidden_global_offset_z
      - .offset:         256
        .size:           2
        .value_kind:     hidden_grid_dims
      - .offset:         280
        .size:           8
        .value_kind:     hidden_multigrid_sync_arg
      - .offset:         312
        .size:           4
        .value_kind:     hidden_dynamic_lds_size
    .group_segment_fixed_size: 0
    .kernarg_segment_align: 8
    .kernarg_segment_size: 448
    .language:       OpenCL C
    .language_version:
      - 2
      - 0
    .max_flat_workgroup_size: 512
    .name:           _Z4mega6Params
    .private_segment_fixed_size: 0
    .sgpr_count:     106
    .sgpr_spill_count: 330
    .symbol:         _Z4mega6Params.kd
    .uniform_work_group_size: 1
    .uses_dynamic_stack: false
    .vgpr_count:     254
    .vgpr_spill_count: 0
    .wavefront_size: 64
